# v19: v16 + residual (Stream-K) epilogue batches 2/3 X rows and partial rows loaded one batch ahead into dead accumulator registers
# speedup vs baseline: 1.0090x; 1.0090x over previous
;     __device__ __forceinline__ void operator()(const f32x4 (&acc)[2][2][4][2], const Unit& u, int wr, int wc, int fr, int fq) const {
;     ...
;                 u32x4 xin[2][2];
; #pragma unroll
;                 for (int mm = 0; mm < 2; ++mm)
; #pragma unroll
;                     for (int bj = 0; bj < 2; ++bj) xin[mm][bj] = *(const u32x4*)(X + (size_t)(row0 + ai * HALF + (mp * 2 + mm) * 16) * DM + col0 + bj * HALF);
;                 f32x4 pv[2][2][2];
; #pragma unroll
;                 for (int mm = 0; mm < 2; ++mm)
; #pragma unroll
;                     for (int bj = 0; bj < 2; ++bj)
; #pragma unroll
;                         for (int n = 0; n < 2; ++n) pv[mm][bj][n] = (f32x4){0.f, 0.f, 0.f, 0.f};
;                 if (src) {
;                     u32x4 pc[2][2];
;     ...
;                     asm volatile("global_load_dwordx4 %0, %4, off sc1\n\tglobal_load_dwordx4 %1, %5, off sc1\n\tglobal_load_dwordx4 %2, %6, off sc1\n\tglobal_load_dwordx4 %3, %7, off sc1\n\ts_waitcnt vmcnt(0)"
;                                  : "=&v"(pc[0][0]), "=&v"(pc[0][1]), "=&v"(pc[1][0]), "=&v"(pc[1][1])
;                                  : "v"(src + CI(0, 0)), "v"(src + CI(0, 1)), "v"(src + CI(1, 0)), "v"(src + CI(1, 1))
;                                  : "memory");
;     ...
; #pragma unroll
;                     for (int mm = 0; mm < 2; ++mm)
; #pragma unroll
;                         for (int bj = 0; bj < 2; ++bj) { float f[8]; unpack8(pc[mm][bj], f); pv[mm][bj][0] = (f32x4){f[0], f[1], f[2], f[3]}; pv[mm][bj][1] = (f32x4){f[4], f[5], f[6], f[7]}; }
;                 }
; #pragma unroll
;                 for (int mm = 0; mm < 2; ++mm) {
;                     const int m = mp * 2 + mm;
;                     const int row = row0 + ai * HALF + m * 16;
;                     float s = 0.f;
; #pragma unroll
;                     for (int bj = 0; bj < 2; ++bj) {
;                         u32x4* px = (u32x4*)(X + (size_t)row * DM + col0 + bj * HALF);
;                         float xo[8]; unpack8(xin[mm][bj], xo);
;                         const f32x4 a0 = acc[ai][bj][m][0] + pv[mm][bj][0], a1 = acc[ai][bj][m][1] + pv[mm][bj][1];
;                         u32x4 w;
;                         w.x = cvt_pk(xo[0] + scale * a0[0], xo[1] + scale * a0[1]); w.y = cvt_pk(xo[2] + scale * a0[2], xo[3] + scale * a0[3]);
.LBB0_411:
	s_or_b64 exec, exec, s[12:13]
	s_waitcnt vmcnt(0)
	s_mov_b64 s[30:31], 0x40000
	v_lshl_add_u64 v[250:251], v[174:175], 0, s[30:31]
	v_lshl_add_u64 v[250:251], v[172:173], 0, v[250:251]
	global_load_dwordx4 v[80:83], v[250:251], off
	global_load_dwordx4 v[84:87], v[250:251], off offset:256
	s_mov_b64 s[30:31], 0x48000
	v_lshl_add_u64 v[252:253], v[174:175], 0, s[30:31]
	v_lshl_add_u64 v[252:253], v[172:173], 0, v[252:253]
	global_load_dwordx4 v[88:91], v[252:253], off
	global_load_dwordx4 v[92:95], v[252:253], off offset:256
	s_and_saveexec_b64 s[12:13], vcc
	s_mov_b64 s[30:31], 0x2000
	v_lshl_add_u64 v[250:251], v[170:171], 0, s[30:31]
	global_load_dwordx4 v[112:115], v[250:251], off sc1
	s_mov_b64 s[30:31], 0x3000
	v_lshl_add_u64 v[252:253], v[170:171], 0, s[30:31]
	global_load_dwordx4 v[116:119], v[252:253], off sc1
	s_mov_b64 s[30:31], 0x2400
	v_lshl_add_u64 v[250:251], v[170:171], 0, s[30:31]
	global_load_dwordx4 v[120:123], v[250:251], off sc1
	s_mov_b64 s[30:31], 0x3400
	v_lshl_add_u64 v[252:253], v[170:171], 0, s[30:31]
	global_load_dwordx4 v[124:127], v[252:253], off sc1
	s_or_b64 exec, exec, s[12:13]
	v_lshlrev_b32_e32 v214, 16, v140
	v_and_b32_e32 v215, 0xffff0000, v140
	v_lshlrev_b32_e32 v244, 16, v141
	v_and_b32_e32 v245, 0xffff0000, v141
	v_and_b32_e32 v247, 0xffff0000, v142
	v_pk_add_f32 v[140:141], v[108:109], v[208:209]
	v_pk_add_f32 v[204:205], v[104:105], v[204:205]
	v_lshlrev_b32_e32 v246, 16, v142
	v_fmac_f32_e32 v214, 0.5, v140
	v_fmac_f32_e32 v215, 0.5, v141
	v_cvt_pk_bf16_f32 v140, v214, v215
	v_fmac_f32_e32 v247, 0.5, v205
	v_and_b32_e32 v205, 0xffff0000, v140
	v_lshlrev_b32_e32 v248, 16, v143
	v_and_b32_e32 v249, 0xffff0000, v143
	v_pk_add_f32 v[142:143], v[110:111], v[210:211]
	v_pk_add_f32 v[206:207], v[106:107], v[206:207]
	v_fmac_f32_e32 v246, 0.5, v204
	v_lshlrev_b32_e32 v204, 16, v140
	v_mul_f32_e32 v205, v205, v205
	v_fmac_f32_e32 v244, 0.5, v142
	v_fmac_f32_e32 v245, 0.5, v143
	v_cvt_pk_bf16_f32 v141, v244, v245
	v_fmac_f32_e32 v248, 0.5, v206
	v_lshlrev_b32_e32 v206, 16, v141
	v_fmac_f32_e32 v205, v204, v204
	v_fmac_f32_e32 v249, 0.5, v207
	v_and_b32_e32 v207, 0xffff0000, v141
	v_fmac_f32_e32 v205, v206, v206
	v_cvt_pk_bf16_f32 v142, v246, v247
	v_fmac_f32_e32 v205, v207, v207
	v_lshlrev_b32_e32 v208, 16, v142
	v_and_b32_e32 v209, 0xffff0000, v142
	v_fmac_f32_e32 v205, v208, v208
	v_cvt_pk_bf16_f32 v143, v248, v249
	v_fmac_f32_e32 v205, v209, v209
	v_lshlrev_b32_e32 v210, 16, v143
	v_and_b32_e32 v211, 0xffff0000, v143
	v_fmac_f32_e32 v205, v210, v210
	v_fmac_f32_e32 v205, v211, v211
	v_lshlrev_b32_e32 v204, 16, v136
	v_and_b32_e32 v206, 0xffff0000, v136
	v_lshlrev_b32_e32 v207, 16, v137
	v_and_b32_e32 v208, 0xffff0000, v137
	v_lshlrev_b32_e32 v209, 16, v138
	v_and_b32_e32 v210, 0xffff0000, v138
	v_lshlrev_b32_e32 v211, 16, v139
	v_and_b32_e32 v214, 0xffff0000, v139
	v_pk_add_f32 v[136:137], v[78:79], v[202:203]
	v_pk_add_f32 v[138:139], v[76:77], v[200:201]
	v_pk_add_f32 v[200:201], v[74:75], v[198:199]
	v_pk_add_f32 v[198:199], v[72:73], v[196:197]
	v_fmac_f32_e32 v204, 0.5, v138
	v_fmac_f32_e32 v206, 0.5, v139
	v_cvt_pk_bf16_f32 v196, v204, v206
	v_fmac_f32_e32 v207, 0.5, v136
	v_lshlrev_b32_e32 v136, 16, v196
	v_fmac_f32_e32 v208, 0.5, v137
	v_and_b32_e32 v137, 0xffff0000, v196
	v_fmac_f32_e32 v205, v136, v136
	v_cvt_pk_bf16_f32 v197, v207, v208
	v_fmac_f32_e32 v205, v137, v137
	v_lshlrev_b32_e32 v138, 16, v197
	v_and_b32_e32 v139, 0xffff0000, v197
	v_fmac_f32_e32 v205, v138, v138
	v_fmac_f32_e32 v209, 0.5, v198
	v_fmac_f32_e32 v210, 0.5, v199
	v_cvt_pk_bf16_f32 v198, v209, v210
	v_fmac_f32_e32 v211, 0.5, v200
	v_lshlrev_b32_e32 v200, 16, v198
	v_fmac_f32_e32 v205, v139, v139
	v_fmac_f32_e32 v214, 0.5, v201
	v_and_b32_e32 v201, 0xffff0000, v198
	v_fmac_f32_e32 v205, v200, v200
	v_cvt_pk_bf16_f32 v199, v211, v214
	v_fmac_f32_e32 v205, v201, v201
	v_lshlrev_b32_e32 v202, 16, v199
	v_and_b32_e32 v203, 0xffff0000, v199
	v_fmac_f32_e32 v205, v202, v202
	v_fmac_f32_e32 v205, v203, v203
	ds_bpermute_b32 v136, v237, v205
	v_lshl_add_u64 v[138:139], s[28:29], 0, v[186:187]
	v_lshl_add_u64 v[138:139], v[168:169], 1, v[138:139]
	global_store_dwordx4 v[138:139], v[140:143], off
	global_store_dwordx4 v[138:139], v[196:199], off offset:256
	s_waitcnt lgkmcnt(0)
	v_add_f32_e32 v136, v205, v136
	ds_bpermute_b32 v137, v238, v136
	s_and_saveexec_b64 s[12:13], s[8:9]
	s_cbranch_execz .LBB0_413
	s_waitcnt lgkmcnt(0)
	v_add_f32_e32 v138, v136, v137
	v_lshl_add_u64 v[136:137], v[166:167], 2, s[6:7]
	global_atomic_add_f32 v[136:137], v138, off offset:128
;     __device__ __forceinline__ void operator()(const f32x4 (&acc)[2][2][4][2], const Unit& u, int wr, int wc, int fr, int fq) const {
;     ...
;                 u32x4 xin[2][2];
; #pragma unroll
;                 for (int mm = 0; mm < 2; ++mm)
; #pragma unroll
;                     for (int bj = 0; bj < 2; ++bj) xin[mm][bj] = *(const u32x4*)(X + (size_t)(row0 + ai * HALF + (mp * 2 + mm) * 16) * DM + col0 + bj * HALF);
;                 f32x4 pv[2][2][2];
; #pragma unroll
;                 for (int mm = 0; mm < 2; ++mm)
; #pragma unroll
;                     for (int bj = 0; bj < 2; ++bj)
; #pragma unroll
;                         for (int n = 0; n < 2; ++n) pv[mm][bj][n] = (f32x4){0.f, 0.f, 0.f, 0.f};
;                 if (src) {
;                     u32x4 pc[2][2];
;     ...
;                     asm volatile("global_load_dwordx4 %0, %4, off sc1\n\tglobal_load_dwordx4 %1, %5, off sc1\n\tglobal_load_dwordx4 %2, %6, off sc1\n\tglobal_load_dwordx4 %3, %7, off sc1\n\ts_waitcnt vmcnt(0)"
;                                  : "=&v"(pc[0][0]), "=&v"(pc[0][1]), "=&v"(pc[1][0]), "=&v"(pc[1][1])
;                                  : "v"(src + CI(0, 0)), "v"(src + CI(0, 1)), "v"(src + CI(1, 0)), "v"(src + CI(1, 1))
;                                  : "memory");
;     ...
; #pragma unroll
;                     for (int mm = 0; mm < 2; ++mm)
; #pragma unroll
;                         for (int bj = 0; bj < 2; ++bj) { float f[8]; unpack8(pc[mm][bj], f); pv[mm][bj][0] = (f32x4){f[0], f[1], f[2], f[3]}; pv[mm][bj][1] = (f32x4){f[4], f[5], f[6], f[7]}; }
;                 }
; #pragma unroll
;                 for (int mm = 0; mm < 2; ++mm) {
;                     const int m = mp * 2 + mm;
;                     const int row = row0 + ai * HALF + m * 16;
;                     float s = 0.f;
; #pragma unroll
;                     for (int bj = 0; bj < 2; ++bj) {
;                         u32x4* px = (u32x4*)(X + (size_t)row * DM + col0 + bj * HALF);
;                         float xo[8]; unpack8(xin[mm][bj], xo);
;                         const f32x4 a0 = acc[ai][bj][m][0] + pv[mm][bj][0], a1 = acc[ai][bj][m][1] + pv[mm][bj][1];
;                         u32x4 w;
;                         w.x = cvt_pk(xo[0] + scale * a0[0], xo[1] + scale * a0[1]); w.y = cvt_pk(xo[2] + scale * a0[2], xo[3] + scale * a0[3]);
.LBB0_413:
	s_or_b64 exec, exec, s[12:13]
	v_lshlrev_b32_e32 v140, 16, v132
	v_and_b32_e32 v141, 0xffff0000, v132
	v_lshlrev_b32_e32 v142, 16, v133
	v_and_b32_e32 v143, 0xffff0000, v133
	v_lshlrev_b32_e32 v186, 16, v134
	v_and_b32_e32 v197, 0xffff0000, v135
	v_pk_add_f32 v[132:133], v[100:101], v[192:193]
	s_waitcnt lgkmcnt(0)
	v_pk_add_f32 v[136:137], v[98:99], v[190:191]
	v_pk_add_f32 v[138:139], v[96:97], v[188:189]
	v_and_b32_e32 v187, 0xffff0000, v134
	v_lshlrev_b32_e32 v196, 16, v135
	v_pk_add_f32 v[134:135], v[102:103], v[194:195]
	v_fmac_f32_e32 v140, 0.5, v132
	v_fmac_f32_e32 v141, 0.5, v133
	v_cvt_pk_bf16_f32 v132, v140, v141
	v_fmac_f32_e32 v186, 0.5, v138
	v_fmac_f32_e32 v197, 0.5, v137
	v_and_b32_e32 v137, 0xffff0000, v132
	v_fmac_f32_e32 v142, 0.5, v134
	v_fmac_f32_e32 v187, 0.5, v139
	v_cvt_pk_bf16_f32 v134, v186, v187
	v_fmac_f32_e32 v196, 0.5, v136
	v_lshlrev_b32_e32 v136, 16, v132
	v_mul_f32_e32 v186, v137, v137
	v_fmac_f32_e32 v143, 0.5, v135
	v_cvt_pk_bf16_f32 v133, v142, v143
	v_fmac_f32_e32 v186, v136, v136
	v_lshlrev_b32_e32 v138, 16, v133
	v_and_b32_e32 v139, 0xffff0000, v133
	v_fmac_f32_e32 v186, v138, v138
	v_lshlrev_b32_e32 v140, 16, v134
	v_fmac_f32_e32 v186, v139, v139
	v_and_b32_e32 v141, 0xffff0000, v134
	v_fmac_f32_e32 v186, v140, v140
	v_cvt_pk_bf16_f32 v135, v196, v197
	v_fmac_f32_e32 v186, v141, v141
	v_lshlrev_b32_e32 v142, 16, v135
	v_and_b32_e32 v143, 0xffff0000, v135
	v_fmac_f32_e32 v186, v142, v142
	v_lshlrev_b32_e32 v136, 16, v128
	v_lshlrev_b32_e32 v187, 16, v130
	v_and_b32_e32 v188, 0xffff0000, v130
	v_lshlrev_b32_e32 v189, 16, v131
	v_and_b32_e32 v190, 0xffff0000, v131
	v_pk_add_f32 v[130:131], v[68:69], v[182:183]
	v_fmac_f32_e32 v186, v143, v143
	v_and_b32_e32 v137, 0xffff0000, v128
	v_lshlrev_b32_e32 v142, 16, v129
	v_and_b32_e32 v143, 0xffff0000, v129
	v_pk_add_f32 v[128:129], v[70:71], v[184:185]
	v_fmac_f32_e32 v136, 0.5, v130
	v_fmac_f32_e32 v137, 0.5, v131
	v_cvt_pk_bf16_f32 v136, v136, v137
	v_fmac_f32_e32 v142, 0.5, v128
	v_lshlrev_b32_e32 v128, 16, v136
	v_fmac_f32_e32 v143, 0.5, v129
	v_and_b32_e32 v129, 0xffff0000, v136
	v_fmac_f32_e32 v186, v128, v128
	v_cvt_pk_bf16_f32 v137, v142, v143
	v_fmac_f32_e32 v186, v129, v129
	v_lshlrev_b32_e32 v130, 16, v137
	v_pk_add_f32 v[140:141], v[66:67], v[180:181]
	v_pk_add_f32 v[138:139], v[64:65], v[178:179]
	v_and_b32_e32 v131, 0xffff0000, v137
	v_fmac_f32_e32 v186, v130, v130
	v_fmac_f32_e32 v187, 0.5, v138
	v_fmac_f32_e32 v188, 0.5, v139
	v_cvt_pk_bf16_f32 v138, v187, v188
	v_fmac_f32_e32 v189, 0.5, v140
	v_lshlrev_b32_e32 v140, 16, v138
	v_fmac_f32_e32 v186, v131, v131
	v_fmac_f32_e32 v190, 0.5, v141
	v_and_b32_e32 v141, 0xffff0000, v138
	v_fmac_f32_e32 v186, v140, v140
	v_cvt_pk_bf16_f32 v139, v189, v190
	v_fmac_f32_e32 v186, v141, v141
	v_lshlrev_b32_e32 v142, 16, v139
	v_and_b32_e32 v143, 0xffff0000, v139
	v_fmac_f32_e32 v186, v142, v142
	v_fmac_f32_e32 v186, v143, v143
	ds_bpermute_b32 v128, v237, v186
	v_lshl_add_u64 v[130:131], s[28:29], 0, v[176:177]
	v_lshl_add_u64 v[130:131], v[168:169], 1, v[130:131]
	global_store_dwordx4 v[130:131], v[132:135], off
	global_store_dwordx4 v[130:131], v[136:139], off offset:256
	s_waitcnt lgkmcnt(0)
	v_add_f32_e32 v128, v186, v128
	ds_bpermute_b32 v129, v238, v128
	s_and_saveexec_b64 s[12:13], s[8:9]
	s_cbranch_execz .LBB0_415
	s_waitcnt lgkmcnt(0)
	v_add_f32_e32 v130, v128, v129
	v_lshl_add_u64 v[128:129], v[166:167], 2, s[6:7]
	global_atomic_add_f32 v[128:129], v130, off offset:192
.LBB0_415:
	s_or_b64 exec, exec, s[12:13]
	s_waitcnt vmcnt(4)
	s_mov_b64 s[12:13], 0x40000
	v_lshl_add_u64 v[186:187], v[174:175], 0, s[12:13]
	s_mov_b64 s[12:13], 0x48000
	s_waitcnt lgkmcnt(0)
	v_lshl_add_u64 v[128:129], v[172:173], 0, v[186:187]
	v_lshl_add_u64 v[176:177], v[174:175], 0, s[12:13]
	v_lshl_add_u64 v[128:129], v[172:173], 0, v[176:177]
	s_nop 0
	v_mov_b32_e32 v140, v80
	v_mov_b32_e32 v141, v81
	v_mov_b32_e32 v142, v82
	v_mov_b32_e32 v143, v83
	v_mov_b32_e32 v136, v84
	v_mov_b32_e32 v137, v85
	v_mov_b32_e32 v138, v86
	v_mov_b32_e32 v139, v87
	v_mov_b32_e32 v132, v88
	v_mov_b32_e32 v133, v89
	v_mov_b32_e32 v134, v90
	v_mov_b32_e32 v135, v91
	v_mov_b32_e32 v128, v92
	v_mov_b32_e32 v129, v93
	v_mov_b32_e32 v130, v94
	v_mov_b32_e32 v131, v95
	v_mov_b32_e32 v178, 0
	v_mov_b32_e32 v179, 0
	v_mov_b32_e32 v180, 0
	v_mov_b32_e32 v181, 0
	v_mov_b32_e32 v182, 0
	v_mov_b32_e32 v183, 0
	v_mov_b32_e32 v184, 0
	v_mov_b32_e32 v185, 0
	v_mov_b32_e32 v188, 0
	v_mov_b32_e32 v189, 0
	v_mov_b32_e32 v190, 0
	v_mov_b32_e32 v191, 0
	v_mov_b32_e32 v192, 0
	v_mov_b32_e32 v193, 0
	v_mov_b32_e32 v194, 0
	v_mov_b32_e32 v195, 0
	v_mov_b32_e32 v196, 0
	v_mov_b32_e32 v197, 0
	v_mov_b32_e32 v198, 0
	v_mov_b32_e32 v199, 0
	v_mov_b32_e32 v200, 0
	v_mov_b32_e32 v201, 0
	v_mov_b32_e32 v202, 0
	v_mov_b32_e32 v203, 0
	v_mov_b32_e32 v204, 0
	v_mov_b32_e32 v205, 0
	v_mov_b32_e32 v206, 0
	v_mov_b32_e32 v207, 0
	v_mov_b32_e32 v208, 0
	v_mov_b32_e32 v209, 0
	v_mov_b32_e32 v210, 0
	v_mov_b32_e32 v211, 0
	s_and_saveexec_b64 s[12:13], vcc
	s_cbranch_execz .LBB0_417
	s_mov_b64 s[30:31], 0x2000
	v_lshl_add_u64 v[192:193], v[170:171], 0, s[30:31]
	s_mov_b64 s[30:31], 0x3000
	v_lshl_add_u64 v[194:195], v[170:171], 0, s[30:31]
	s_mov_b64 s[30:31], 0x2400
	v_lshl_add_u64 v[196:197], v[170:171], 0, s[30:31]
	s_mov_b64 s[30:31], 0x3400
	v_lshl_add_u64 v[198:199], v[170:171], 0, s[30:31]
	v_mov_b32_e32 v178, v112
	v_mov_b32_e32 v179, v113
	v_mov_b32_e32 v180, v114
	v_mov_b32_e32 v181, v115
	v_mov_b32_e32 v182, v116
	v_mov_b32_e32 v183, v117
	v_mov_b32_e32 v184, v118
	v_mov_b32_e32 v185, v119
	v_mov_b32_e32 v188, v120
	v_mov_b32_e32 v189, v121
	v_mov_b32_e32 v190, v122
	v_mov_b32_e32 v191, v123
	v_mov_b32_e32 v244, v124
	v_mov_b32_e32 v245, v125
	v_mov_b32_e32 v246, v126
	v_mov_b32_e32 v247, v127
	s_nop 0
	v_lshlrev_b32_e32 v208, 16, v178
	v_and_b32_e32 v209, 0xffff0000, v178
	v_lshlrev_b32_e32 v210, 16, v179
	v_and_b32_e32 v211, 0xffff0000, v179
	v_lshlrev_b32_e32 v204, 16, v180
	v_and_b32_e32 v205, 0xffff0000, v180
	v_lshlrev_b32_e32 v206, 16, v181
	v_and_b32_e32 v207, 0xffff0000, v181
	v_lshlrev_b32_e32 v200, 16, v182
	v_and_b32_e32 v201, 0xffff0000, v182
	v_lshlrev_b32_e32 v202, 16, v183
	v_and_b32_e32 v203, 0xffff0000, v183
	v_lshlrev_b32_e32 v196, 16, v184
	v_and_b32_e32 v197, 0xffff0000, v184
	v_lshlrev_b32_e32 v198, 16, v185
	v_and_b32_e32 v199, 0xffff0000, v185
	v_lshlrev_b32_e32 v192, 16, v188
	v_and_b32_e32 v193, 0xffff0000, v188
	v_lshlrev_b32_e32 v194, 16, v189
	v_and_b32_e32 v195, 0xffff0000, v189
	v_lshlrev_b32_e32 v188, 16, v190
	v_and_b32_e32 v189, 0xffff0000, v190
	v_lshlrev_b32_e32 v190, 16, v191
	v_and_b32_e32 v191, 0xffff0000, v191
	v_lshlrev_b32_e32 v182, 16, v244
	v_and_b32_e32 v183, 0xffff0000, v244
	v_lshlrev_b32_e32 v184, 16, v245
	v_and_b32_e32 v185, 0xffff0000, v245
	v_lshlrev_b32_e32 v178, 16, v246
	v_and_b32_e32 v179, 0xffff0000, v246
	v_lshlrev_b32_e32 v180, 16, v247
	v_and_b32_e32 v181, 0xffff0000, v247
;     __device__ __forceinline__ void operator()(const f32x4 (&acc)[2][2][4][2], const Unit& u, int wr, int wc, int fr, int fq) const {
;     ...
;                 u32x4 xin[2][2];
; #pragma unroll
;                 for (int mm = 0; mm < 2; ++mm)
; #pragma unroll
;                     for (int bj = 0; bj < 2; ++bj) xin[mm][bj] = *(const u32x4*)(X + (size_t)(row0 + ai * HALF + (mp * 2 + mm) * 16) * DM + col0 + bj * HALF);
;                 f32x4 pv[2][2][2];
; #pragma unroll
;                 for (int mm = 0; mm < 2; ++mm)
; #pragma unroll
;                     for (int bj = 0; bj < 2; ++bj)
; #pragma unroll
;                         for (int n = 0; n < 2; ++n) pv[mm][bj][n] = (f32x4){0.f, 0.f, 0.f, 0.f};
;                 if (src) {
;                     u32x4 pc[2][2];
;     ...
;                     asm volatile("global_load_dwordx4 %0, %4, off sc1\n\tglobal_load_dwordx4 %1, %5, off sc1\n\tglobal_load_dwordx4 %2, %6, off sc1\n\tglobal_load_dwordx4 %3, %7, off sc1\n\ts_waitcnt vmcnt(0)"
;                                  : "=&v"(pc[0][0]), "=&v"(pc[0][1]), "=&v"(pc[1][0]), "=&v"(pc[1][1])
;                                  : "v"(src + CI(0, 0)), "v"(src + CI(0, 1)), "v"(src + CI(1, 0)), "v"(src + CI(1, 1))
;                                  : "memory");
;     ...
; #pragma unroll
;                     for (int mm = 0; mm < 2; ++mm)
; #pragma unroll
;                         for (int bj = 0; bj < 2; ++bj) { float f[8]; unpack8(pc[mm][bj], f); pv[mm][bj][0] = (f32x4){f[0], f[1], f[2], f[3]}; pv[mm][bj][1] = (f32x4){f[4], f[5], f[6], f[7]}; }
;                 }
; #pragma unroll
;                 for (int mm = 0; mm < 2; ++mm) {
;                     const int m = mp * 2 + mm;
;                     const int row = row0 + ai * HALF + m * 16;
;                     float s = 0.f;
; #pragma unroll
;                     for (int bj = 0; bj < 2; ++bj) {
;                         u32x4* px = (u32x4*)(X + (size_t)row * DM + col0 + bj * HALF);
;                         float xo[8]; unpack8(xin[mm][bj], xo);
;                         const f32x4 a0 = acc[ai][bj][m][0] + pv[mm][bj][0], a1 = acc[ai][bj][m][1] + pv[mm][bj][1];
;                         u32x4 w;
;                         w.x = cvt_pk(xo[0] + scale * a0[0], xo[1] + scale * a0[1]); w.y = cvt_pk(xo[2] + scale * a0[2], xo[3] + scale * a0[3]);
.LBB0_417:
	s_or_b64 exec, exec, s[12:13]
	s_mov_b64 s[30:31], 0x50000
	v_lshl_add_u64 v[250:251], v[174:175], 0, s[30:31]
	v_lshl_add_u64 v[250:251], v[172:173], 0, v[250:251]
	global_load_dwordx4 v[64:67], v[250:251], off
	global_load_dwordx4 v[68:71], v[250:251], off offset:256
	s_mov_b64 s[30:31], 0x58000
	v_lshl_add_u64 v[252:253], v[174:175], 0, s[30:31]
	v_lshl_add_u64 v[252:253], v[172:173], 0, v[252:253]
	global_load_dwordx4 v[72:75], v[252:253], off
	global_load_dwordx4 v[76:79], v[252:253], off offset:256
	s_and_saveexec_b64 s[12:13], vcc
	s_mov_b64 s[30:31], 0x2800
	v_lshl_add_u64 v[250:251], v[170:171], 0, s[30:31]
	global_load_dwordx4 v[96:99], v[250:251], off sc1
	s_mov_b64 s[30:31], 0x3800
	v_lshl_add_u64 v[252:253], v[170:171], 0, s[30:31]
	global_load_dwordx4 v[100:103], v[252:253], off sc1
	s_mov_b64 s[30:31], 0x2c00
	v_lshl_add_u64 v[250:251], v[170:171], 0, s[30:31]
	global_load_dwordx4 v[104:107], v[250:251], off sc1
	s_mov_b64 s[30:31], 0x3c00
	v_lshl_add_u64 v[252:253], v[170:171], 0, s[30:31]
	global_load_dwordx4 v[108:111], v[252:253], off sc1
	s_or_b64 exec, exec, s[12:13]
	v_lshlrev_b32_e32 v214, 16, v140
	v_and_b32_e32 v215, 0xffff0000, v140
	v_lshlrev_b32_e32 v244, 16, v141
	v_and_b32_e32 v245, 0xffff0000, v141
	v_and_b32_e32 v247, 0xffff0000, v142
	v_pk_add_f32 v[140:141], v[60:61], v[208:209]
	v_pk_add_f32 v[204:205], v[56:57], v[204:205]
	v_lshlrev_b32_e32 v246, 16, v142
	v_fmac_f32_e32 v214, 0.5, v140
	v_fmac_f32_e32 v215, 0.5, v141
	v_cvt_pk_bf16_f32 v140, v214, v215
	v_fmac_f32_e32 v247, 0.5, v205
	v_and_b32_e32 v205, 0xffff0000, v140
	v_lshlrev_b32_e32 v248, 16, v143
	v_and_b32_e32 v249, 0xffff0000, v143
	v_pk_add_f32 v[142:143], v[62:63], v[210:211]
	v_pk_add_f32 v[206:207], v[58:59], v[206:207]
	v_fmac_f32_e32 v246, 0.5, v204
	v_lshlrev_b32_e32 v204, 16, v140
	v_mul_f32_e32 v205, v205, v205
	v_fmac_f32_e32 v244, 0.5, v142
	v_fmac_f32_e32 v245, 0.5, v143
	v_cvt_pk_bf16_f32 v141, v244, v245
	v_fmac_f32_e32 v248, 0.5, v206
	v_lshlrev_b32_e32 v206, 16, v141
	v_fmac_f32_e32 v205, v204, v204
	v_fmac_f32_e32 v249, 0.5, v207
	v_and_b32_e32 v207, 0xffff0000, v141
	v_fmac_f32_e32 v205, v206, v206
	v_cvt_pk_bf16_f32 v142, v246, v247
	v_fmac_f32_e32 v205, v207, v207
	v_lshlrev_b32_e32 v208, 16, v142
	v_and_b32_e32 v209, 0xffff0000, v142
	v_fmac_f32_e32 v205, v208, v208
	v_cvt_pk_bf16_f32 v143, v248, v249
	v_fmac_f32_e32 v205, v209, v209
	v_lshlrev_b32_e32 v210, 16, v143
	v_and_b32_e32 v211, 0xffff0000, v143
	v_fmac_f32_e32 v205, v210, v210
	v_fmac_f32_e32 v205, v211, v211
	v_lshlrev_b32_e32 v204, 16, v136
	v_and_b32_e32 v206, 0xffff0000, v136
	v_lshlrev_b32_e32 v207, 16, v137
	v_and_b32_e32 v208, 0xffff0000, v137
	v_lshlrev_b32_e32 v209, 16, v138
	v_and_b32_e32 v210, 0xffff0000, v138
	v_lshlrev_b32_e32 v211, 16, v139
	v_and_b32_e32 v214, 0xffff0000, v139
	v_pk_add_f32 v[136:137], v[30:31], v[202:203]
	v_pk_add_f32 v[138:139], v[28:29], v[200:201]
	v_pk_add_f32 v[200:201], v[26:27], v[198:199]
	v_pk_add_f32 v[198:199], v[24:25], v[196:197]
	v_fmac_f32_e32 v204, 0.5, v138
	v_fmac_f32_e32 v206, 0.5, v139
	v_cvt_pk_bf16_f32 v196, v204, v206
	v_fmac_f32_e32 v207, 0.5, v136
	v_lshlrev_b32_e32 v136, 16, v196
	v_fmac_f32_e32 v208, 0.5, v137
	v_and_b32_e32 v137, 0xffff0000, v196
	v_fmac_f32_e32 v205, v136, v136
	v_cvt_pk_bf16_f32 v197, v207, v208
	v_fmac_f32_e32 v205, v137, v137
	v_lshlrev_b32_e32 v138, 16, v197
	v_and_b32_e32 v139, 0xffff0000, v197
	v_fmac_f32_e32 v205, v138, v138
	v_fmac_f32_e32 v209, 0.5, v198
	v_fmac_f32_e32 v210, 0.5, v199
	v_cvt_pk_bf16_f32 v198, v209, v210
	v_fmac_f32_e32 v211, 0.5, v200
	v_lshlrev_b32_e32 v200, 16, v198
	v_fmac_f32_e32 v205, v139, v139
	v_fmac_f32_e32 v214, 0.5, v201
	v_and_b32_e32 v201, 0xffff0000, v198
	v_fmac_f32_e32 v205, v200, v200
	v_cvt_pk_bf16_f32 v199, v211, v214
	v_fmac_f32_e32 v205, v201, v201
	v_lshlrev_b32_e32 v202, 16, v199
	v_and_b32_e32 v203, 0xffff0000, v199
	v_fmac_f32_e32 v205, v202, v202
	v_fmac_f32_e32 v205, v203, v203
	ds_bpermute_b32 v136, v237, v205
	v_lshl_add_u64 v[138:139], s[28:29], 0, v[186:187]
	v_lshl_add_u64 v[138:139], v[168:169], 1, v[138:139]
	global_store_dwordx4 v[138:139], v[140:143], off
	global_store_dwordx4 v[138:139], v[196:199], off offset:256
	s_waitcnt lgkmcnt(0)
	v_add_f32_e32 v136, v205, v136
	ds_bpermute_b32 v137, v238, v136
	s_and_saveexec_b64 s[12:13], s[8:9]
	s_cbranch_execz .LBB0_419
	s_waitcnt lgkmcnt(0)
	v_add_f32_e32 v138, v136, v137
	v_lshl_add_u64 v[136:137], v[166:167], 2, s[6:7]
	global_atomic_add_f32 v[136:137], v138, off offset:512
;     __device__ __forceinline__ void operator()(const f32x4 (&acc)[2][2][4][2], const Unit& u, int wr, int wc, int fr, int fq) const {
;     ...
;                 u32x4 xin[2][2];
; #pragma unroll
;                 for (int mm = 0; mm < 2; ++mm)
; #pragma unroll
;                     for (int bj = 0; bj < 2; ++bj) xin[mm][bj] = *(const u32x4*)(X + (size_t)(row0 + ai * HALF + (mp * 2 + mm) * 16) * DM + col0 + bj * HALF);
;                 f32x4 pv[2][2][2];
; #pragma unroll
;                 for (int mm = 0; mm < 2; ++mm)
; #pragma unroll
;                     for (int bj = 0; bj < 2; ++bj)
; #pragma unroll
;                         for (int n = 0; n < 2; ++n) pv[mm][bj][n] = (f32x4){0.f, 0.f, 0.f, 0.f};
;                 if (src) {
;                     u32x4 pc[2][2];
;     ...
;                     asm volatile("global_load_dwordx4 %0, %4, off sc1\n\tglobal_load_dwordx4 %1, %5, off sc1\n\tglobal_load_dwordx4 %2, %6, off sc1\n\tglobal_load_dwordx4 %3, %7, off sc1\n\ts_waitcnt vmcnt(0)"
;                                  : "=&v"(pc[0][0]), "=&v"(pc[0][1]), "=&v"(pc[1][0]), "=&v"(pc[1][1])
;                                  : "v"(src + CI(0, 0)), "v"(src + CI(0, 1)), "v"(src + CI(1, 0)), "v"(src + CI(1, 1))
;                                  : "memory");
;     ...
; #pragma unroll
;                     for (int mm = 0; mm < 2; ++mm)
; #pragma unroll
;                         for (int bj = 0; bj < 2; ++bj) { float f[8]; unpack8(pc[mm][bj], f); pv[mm][bj][0] = (f32x4){f[0], f[1], f[2], f[3]}; pv[mm][bj][1] = (f32x4){f[4], f[5], f[6], f[7]}; }
;                 }
; #pragma unroll
;                 for (int mm = 0; mm < 2; ++mm) {
;                     const int m = mp * 2 + mm;
;                     const int row = row0 + ai * HALF + m * 16;
;                     float s = 0.f;
; #pragma unroll
;                     for (int bj = 0; bj < 2; ++bj) {
;                         u32x4* px = (u32x4*)(X + (size_t)row * DM + col0 + bj * HALF);
;                         float xo[8]; unpack8(xin[mm][bj], xo);
;                         const f32x4 a0 = acc[ai][bj][m][0] + pv[mm][bj][0], a1 = acc[ai][bj][m][1] + pv[mm][bj][1];
;                         u32x4 w;
;                         w.x = cvt_pk(xo[0] + scale * a0[0], xo[1] + scale * a0[1]); w.y = cvt_pk(xo[2] + scale * a0[2], xo[3] + scale * a0[3]);
.LBB0_419:
	s_or_b64 exec, exec, s[12:13]
	v_lshlrev_b32_e32 v140, 16, v132
	v_and_b32_e32 v141, 0xffff0000, v132
	v_lshlrev_b32_e32 v142, 16, v133
	v_and_b32_e32 v143, 0xffff0000, v133
	v_lshlrev_b32_e32 v186, 16, v134
	v_and_b32_e32 v197, 0xffff0000, v135
	v_pk_add_f32 v[132:133], v[52:53], v[192:193]
	s_waitcnt lgkmcnt(0)
	v_pk_add_f32 v[136:137], v[50:51], v[190:191]
	v_pk_add_f32 v[138:139], v[48:49], v[188:189]
	v_and_b32_e32 v187, 0xffff0000, v134
	v_lshlrev_b32_e32 v196, 16, v135
	v_pk_add_f32 v[134:135], v[54:55], v[194:195]
	v_fmac_f32_e32 v140, 0.5, v132
	v_fmac_f32_e32 v141, 0.5, v133
	v_cvt_pk_bf16_f32 v132, v140, v141
	v_fmac_f32_e32 v186, 0.5, v138
	v_fmac_f32_e32 v197, 0.5, v137
	v_and_b32_e32 v137, 0xffff0000, v132
	v_fmac_f32_e32 v142, 0.5, v134
	v_fmac_f32_e32 v187, 0.5, v139
	v_cvt_pk_bf16_f32 v134, v186, v187
	v_fmac_f32_e32 v196, 0.5, v136
	v_lshlrev_b32_e32 v136, 16, v132
	v_mul_f32_e32 v186, v137, v137
	v_fmac_f32_e32 v143, 0.5, v135
	v_cvt_pk_bf16_f32 v133, v142, v143
	v_fmac_f32_e32 v186, v136, v136
	v_lshlrev_b32_e32 v138, 16, v133
	v_and_b32_e32 v139, 0xffff0000, v133
	v_fmac_f32_e32 v186, v138, v138
	v_lshlrev_b32_e32 v140, 16, v134
	v_fmac_f32_e32 v186, v139, v139
	v_and_b32_e32 v141, 0xffff0000, v134
	v_fmac_f32_e32 v186, v140, v140
	v_cvt_pk_bf16_f32 v135, v196, v197
	v_fmac_f32_e32 v186, v141, v141
	v_lshlrev_b32_e32 v142, 16, v135
	v_and_b32_e32 v143, 0xffff0000, v135
	v_fmac_f32_e32 v186, v142, v142
	v_lshlrev_b32_e32 v136, 16, v128
	v_lshlrev_b32_e32 v187, 16, v130
	v_and_b32_e32 v188, 0xffff0000, v130
	v_lshlrev_b32_e32 v189, 16, v131
	v_and_b32_e32 v190, 0xffff0000, v131
	v_pk_add_f32 v[130:131], v[20:21], v[182:183]
	v_fmac_f32_e32 v186, v143, v143
	v_and_b32_e32 v137, 0xffff0000, v128
	v_lshlrev_b32_e32 v142, 16, v129
	v_and_b32_e32 v143, 0xffff0000, v129
	v_pk_add_f32 v[128:129], v[22:23], v[184:185]
	v_fmac_f32_e32 v136, 0.5, v130
	v_fmac_f32_e32 v137, 0.5, v131
	v_cvt_pk_bf16_f32 v136, v136, v137
	v_fmac_f32_e32 v142, 0.5, v128
	v_lshlrev_b32_e32 v128, 16, v136
	v_fmac_f32_e32 v143, 0.5, v129
	v_and_b32_e32 v129, 0xffff0000, v136
	v_fmac_f32_e32 v186, v128, v128
	v_cvt_pk_bf16_f32 v137, v142, v143
	v_fmac_f32_e32 v186, v129, v129
	v_lshlrev_b32_e32 v130, 16, v137
	v_pk_add_f32 v[140:141], v[18:19], v[180:181]
	v_pk_add_f32 v[138:139], v[16:17], v[178:179]
	v_and_b32_e32 v131, 0xffff0000, v137
	v_fmac_f32_e32 v186, v130, v130
	v_fmac_f32_e32 v187, 0.5, v138
	v_fmac_f32_e32 v188, 0.5, v139
	v_cvt_pk_bf16_f32 v138, v187, v188
	v_fmac_f32_e32 v189, 0.5, v140
	v_lshlrev_b32_e32 v140, 16, v138
	v_fmac_f32_e32 v186, v131, v131
	v_fmac_f32_e32 v190, 0.5, v141
	v_and_b32_e32 v141, 0xffff0000, v138
	v_fmac_f32_e32 v186, v140, v140
	v_cvt_pk_bf16_f32 v139, v189, v190
	v_fmac_f32_e32 v186, v141, v141
	v_lshlrev_b32_e32 v142, 16, v139
	v_and_b32_e32 v143, 0xffff0000, v139
	v_fmac_f32_e32 v186, v142, v142
	v_fmac_f32_e32 v186, v143, v143
	ds_bpermute_b32 v128, v237, v186
	v_lshl_add_u64 v[130:131], s[28:29], 0, v[176:177]
	v_lshl_add_u64 v[130:131], v[168:169], 1, v[130:131]
	global_store_dwordx4 v[130:131], v[132:135], off
	global_store_dwordx4 v[130:131], v[136:139], off offset:256
	s_waitcnt lgkmcnt(0)
	v_add_f32_e32 v128, v186, v128
	ds_bpermute_b32 v129, v238, v128
	s_and_saveexec_b64 s[12:13], s[8:9]
	s_cbranch_execz .LBB0_421
	s_waitcnt lgkmcnt(0)
	v_add_f32_e32 v130, v128, v129
	v_lshl_add_u64 v[128:129], v[166:167], 2, s[6:7]
	global_atomic_add_f32 v[128:129], v130, off offset:576
.LBB0_421:
	s_or_b64 exec, exec, s[12:13]
	s_waitcnt vmcnt(4)
	s_mov_b64 s[12:13], 0x50000
	v_lshl_add_u64 v[182:183], v[174:175], 0, s[12:13]
	s_mov_b64 s[12:13], 0x58000
	s_waitcnt lgkmcnt(0)
	v_lshl_add_u64 v[128:129], v[172:173], 0, v[182:183]
	v_lshl_add_u64 v[174:175], v[174:175], 0, s[12:13]
	v_lshl_add_u64 v[128:129], v[172:173], 0, v[174:175]
	s_nop 0
	v_mov_b32_e32 v140, v64
	v_mov_b32_e32 v141, v65
	v_mov_b32_e32 v142, v66
	v_mov_b32_e32 v143, v67
	v_mov_b32_e32 v136, v68
	v_mov_b32_e32 v137, v69
	v_mov_b32_e32 v138, v70
	v_mov_b32_e32 v139, v71
	v_mov_b32_e32 v132, v72
	v_mov_b32_e32 v133, v73
	v_mov_b32_e32 v134, v74
	v_mov_b32_e32 v135, v75
	v_mov_b32_e32 v128, v76
	v_mov_b32_e32 v129, v77
	v_mov_b32_e32 v130, v78
	v_mov_b32_e32 v131, v79
	v_mov_b32_e32 v172, 0
	v_mov_b32_e32 v173, 0
	v_mov_b32_e32 v176, 0
	v_mov_b32_e32 v177, 0
	v_mov_b32_e32 v178, 0
	v_mov_b32_e32 v179, 0
	v_mov_b32_e32 v180, 0
	v_mov_b32_e32 v181, 0
	v_mov_b32_e32 v184, 0
	v_mov_b32_e32 v185, 0
	v_mov_b32_e32 v186, 0
	v_mov_b32_e32 v187, 0
	v_mov_b32_e32 v188, 0
	v_mov_b32_e32 v189, 0
	v_mov_b32_e32 v190, 0
	v_mov_b32_e32 v191, 0
	v_mov_b32_e32 v192, 0
	v_mov_b32_e32 v193, 0
	v_mov_b32_e32 v194, 0
	v_mov_b32_e32 v195, 0
	v_mov_b32_e32 v196, 0
	v_mov_b32_e32 v197, 0
	v_mov_b32_e32 v198, 0
	v_mov_b32_e32 v199, 0
	v_mov_b32_e32 v200, 0
	v_mov_b32_e32 v201, 0
	v_mov_b32_e32 v202, 0
	v_mov_b32_e32 v203, 0
	v_mov_b32_e32 v204, 0
	v_mov_b32_e32 v205, 0
	v_mov_b32_e32 v206, 0
	v_mov_b32_e32 v207, 0
	s_and_saveexec_b64 s[12:13], vcc
	s_cbranch_execz .LBB0_423
	s_mov_b64 s[30:31], 0x2800
	v_lshl_add_u64 v[180:181], v[170:171], 0, s[30:31]
	s_mov_b64 s[30:31], 0x3800
	v_lshl_add_u64 v[188:189], v[170:171], 0, s[30:31]
	s_mov_b64 s[30:31], 0x2c00
	v_lshl_add_u64 v[190:191], v[170:171], 0, s[30:31]
	s_mov_b64 s[30:31], 0x3c00
	v_lshl_add_u64 v[192:193], v[170:171], 0, s[30:31]
	v_mov_b32_e32 v170, v96
	v_mov_b32_e32 v171, v97
	v_mov_b32_e32 v172, v98
	v_mov_b32_e32 v173, v99
	v_mov_b32_e32 v176, v100
	v_mov_b32_e32 v177, v101
	v_mov_b32_e32 v178, v102
	v_mov_b32_e32 v179, v103
	v_mov_b32_e32 v184, v104
	v_mov_b32_e32 v185, v105
	v_mov_b32_e32 v186, v106
	v_mov_b32_e32 v187, v107
	v_mov_b32_e32 v208, v108
	v_mov_b32_e32 v209, v109
	v_mov_b32_e32 v210, v110
	v_mov_b32_e32 v211, v111
	s_nop 0
	v_lshlrev_b32_e32 v204, 16, v170
	v_and_b32_e32 v205, 0xffff0000, v170
	v_lshlrev_b32_e32 v206, 16, v171
	v_and_b32_e32 v207, 0xffff0000, v171
	v_lshlrev_b32_e32 v200, 16, v172
	v_and_b32_e32 v201, 0xffff0000, v172
	v_lshlrev_b32_e32 v202, 16, v173
	v_and_b32_e32 v203, 0xffff0000, v173
	v_lshlrev_b32_e32 v196, 16, v176
	v_and_b32_e32 v197, 0xffff0000, v176
	v_lshlrev_b32_e32 v198, 16, v177
	v_and_b32_e32 v199, 0xffff0000, v177
	v_lshlrev_b32_e32 v192, 16, v178
	v_and_b32_e32 v193, 0xffff0000, v178
	v_lshlrev_b32_e32 v194, 16, v179
	v_and_b32_e32 v195, 0xffff0000, v179
	v_lshlrev_b32_e32 v188, 16, v184
	v_and_b32_e32 v189, 0xffff0000, v184
	v_lshlrev_b32_e32 v190, 16, v185
	v_and_b32_e32 v191, 0xffff0000, v185
	v_lshlrev_b32_e32 v184, 16, v186
	v_and_b32_e32 v185, 0xffff0000, v186
	v_lshlrev_b32_e32 v186, 16, v187
	v_and_b32_e32 v187, 0xffff0000, v187
	v_lshlrev_b32_e32 v178, 16, v208
	v_and_b32_e32 v179, 0xffff0000, v208
	v_lshlrev_b32_e32 v180, 16, v209
	v_and_b32_e32 v181, 0xffff0000, v209
	v_lshlrev_b32_e32 v172, 16, v210
	v_and_b32_e32 v173, 0xffff0000, v210
	v_lshlrev_b32_e32 v176, 16, v211
	v_and_b32_e32 v177, 0xffff0000, v211
; DI unsigned cvt_pk(float lo, float hi) { unsigned r; asm("v_cvt_pk_bf16_f32 %0, %1, %2" : "=v"(r) : "v"(lo), "v"(hi)); return r; }
;     __device__ __forceinline__ void operator()(const f32x4 (&acc)[2][2][4][2], const Unit& u, int wr, int wc, int fr, int fq) const {
;     ...
; #pragma unroll
;                 for (int mm = 0; mm < 2; ++mm) {
;                     const int m = mp * 2 + mm;
;                     const int row = row0 + ai * HALF + m * 16;
;                     float s = 0.f;
; #pragma unroll
;                     for (int bj = 0; bj < 2; ++bj) {
;                         u32x4* px = (u32x4*)(X + (size_t)row * DM + col0 + bj * HALF);
;                         float xo[8]; unpack8(xin[mm][bj], xo);
;                         const f32x4 a0 = acc[ai][bj][m][0] + pv[mm][bj][0], a1 = acc[ai][bj][m][1] + pv[mm][bj][1];
;                         u32x4 w;
;                         w.x = cvt_pk(xo[0] + scale * a0[0], xo[1] + scale * a0[1]); w.y = cvt_pk(xo[2] + scale * a0[2], xo[3] + scale * a0[3]);
;                         w.z = cvt_pk(xo[4] + scale * a1[0], xo[5] + scale * a1[1]); w.w = cvt_pk(xo[6] + scale * a1[2], xo[7] + scale * a1[3]);
;                         *px = w;
;                         float xn[8]; unpack8(w, xn);
; #pragma unroll
;                         for (int j = 0; j < 8; ++j) s += xn[j] * xn[j];
;                     }
;                     s += __shfl_xor(s, 16); s += __shfl_xor(s, 32);
;                     if (fq == 0) unsafeAtomicAdd(ssn + row, s);
;                 }
.LBB0_423:
	s_or_b64 exec, exec, s[12:13]
	v_lshlrev_b32_e32 v208, 16, v140
	v_and_b32_e32 v209, 0xffff0000, v140
	v_lshlrev_b32_e32 v210, 16, v141
	v_and_b32_e32 v211, 0xffff0000, v141
	v_and_b32_e32 v245, 0xffff0000, v143
	v_pk_add_f32 v[140:141], v[44:45], v[204:205]
	v_pk_add_f32 v[170:171], v[42:43], v[202:203]
	v_lshlrev_b32_e32 v244, 16, v143
	v_fmac_f32_e32 v208, 0.5, v140
	v_fmac_f32_e32 v209, 0.5, v141
	v_cvt_pk_bf16_f32 v140, v208, v209
	v_fmac_f32_e32 v245, 0.5, v171
	v_and_b32_e32 v171, 0xffff0000, v140
	v_lshlrev_b32_e32 v214, 16, v142
	v_and_b32_e32 v215, 0xffff0000, v142
	v_pk_add_f32 v[142:143], v[46:47], v[206:207]
	v_pk_add_f32 v[200:201], v[40:41], v[200:201]
	v_fmac_f32_e32 v244, 0.5, v170
	v_lshlrev_b32_e32 v170, 16, v140
	v_mul_f32_e32 v206, v171, v171
	v_fmac_f32_e32 v210, 0.5, v142
	v_fmac_f32_e32 v211, 0.5, v143
	v_cvt_pk_bf16_f32 v141, v210, v211
	v_fmac_f32_e32 v214, 0.5, v200
	v_lshlrev_b32_e32 v200, 16, v141
	v_fmac_f32_e32 v206, v170, v170
	v_fmac_f32_e32 v215, 0.5, v201
	v_and_b32_e32 v201, 0xffff0000, v141
	v_fmac_f32_e32 v206, v200, v200
	v_cvt_pk_bf16_f32 v142, v214, v215
	v_fmac_f32_e32 v206, v201, v201
	v_lshlrev_b32_e32 v202, 16, v142
	v_and_b32_e32 v203, 0xffff0000, v142
	v_fmac_f32_e32 v206, v202, v202
	v_cvt_pk_bf16_f32 v143, v244, v245
	v_fmac_f32_e32 v206, v203, v203
	v_lshlrev_b32_e32 v204, 16, v143
	v_and_b32_e32 v205, 0xffff0000, v143
	v_fmac_f32_e32 v206, v204, v204
	v_fmac_f32_e32 v206, v205, v205
	v_lshlrev_b32_e32 v200, 16, v136
	v_and_b32_e32 v201, 0xffff0000, v136
	v_lshlrev_b32_e32 v202, 16, v137
	v_and_b32_e32 v203, 0xffff0000, v137
	v_lshlrev_b32_e32 v204, 16, v138
	v_and_b32_e32 v205, 0xffff0000, v138
	v_lshlrev_b32_e32 v207, 16, v139
	v_and_b32_e32 v208, 0xffff0000, v139
	v_pk_add_f32 v[136:137], v[14:15], v[198:199]
	v_pk_add_f32 v[138:139], v[12:13], v[196:197]
	v_pk_add_f32 v[170:171], v[10:11], v[194:195]
	v_pk_add_f32 v[194:195], v[8:9], v[192:193]
	v_fmac_f32_e32 v200, 0.5, v138
	v_fmac_f32_e32 v201, 0.5, v139
	v_cvt_pk_bf16_f32 v192, v200, v201
	v_fmac_f32_e32 v202, 0.5, v136
	v_lshlrev_b32_e32 v136, 16, v192
	v_fmac_f32_e32 v203, 0.5, v137
	v_and_b32_e32 v137, 0xffff0000, v192
	v_fmac_f32_e32 v206, v136, v136
	v_cvt_pk_bf16_f32 v193, v202, v203
	v_fmac_f32_e32 v206, v137, v137
	v_lshlrev_b32_e32 v138, 16, v193
	v_and_b32_e32 v139, 0xffff0000, v193
	v_fmac_f32_e32 v206, v138, v138
	v_fmac_f32_e32 v204, 0.5, v194
	v_fmac_f32_e32 v205, 0.5, v195
	v_cvt_pk_bf16_f32 v194, v204, v205
	v_fmac_f32_e32 v207, 0.5, v170
	v_lshlrev_b32_e32 v170, 16, v194
	v_fmac_f32_e32 v206, v139, v139
	v_fmac_f32_e32 v208, 0.5, v171
	v_and_b32_e32 v171, 0xffff0000, v194
	v_fmac_f32_e32 v206, v170, v170
	v_cvt_pk_bf16_f32 v195, v207, v208
	v_fmac_f32_e32 v206, v171, v171
	v_lshlrev_b32_e32 v196, 16, v195
	v_and_b32_e32 v197, 0xffff0000, v195
	v_fmac_f32_e32 v206, v196, v196
	v_fmac_f32_e32 v206, v197, v197
	ds_bpermute_b32 v136, v237, v206
	v_lshl_add_u64 v[138:139], s[28:29], 0, v[182:183]
	v_lshl_add_u64 v[138:139], v[168:169], 1, v[138:139]
	global_store_dwordx4 v[138:139], v[140:143], off
	global_store_dwordx4 v[138:139], v[192:195], off offset:256
	s_waitcnt lgkmcnt(0)
	v_add_f32_e32 v136, v206, v136
	ds_bpermute_b32 v137, v238, v136
	s_and_saveexec_b64 s[12:13], s[8:9]
	s_cbranch_execz .LBB0_425
	s_waitcnt lgkmcnt(0)
	v_add_f32_e32 v138, v136, v137
	v_lshl_add_u64 v[136:137], v[166:167], 2, s[6:7]
	global_atomic_add_f32 v[136:137], v138, off offset:640
.LBB0_425:
	s_or_b64 exec, exec, s[12:13]
	v_lshlrev_b32_e32 v140, 16, v132
	v_and_b32_e32 v141, 0xffff0000, v132
	v_lshlrev_b32_e32 v142, 16, v133
	v_and_b32_e32 v143, 0xffff0000, v133
	v_lshlrev_b32_e32 v170, 16, v134
	v_and_b32_e32 v183, 0xffff0000, v135
	v_pk_add_f32 v[132:133], v[36:37], v[188:189]
	s_waitcnt lgkmcnt(0)
	v_pk_add_f32 v[136:137], v[34:35], v[186:187]
	v_pk_add_f32 v[138:139], v[32:33], v[184:185]
	v_and_b32_e32 v171, 0xffff0000, v134
	v_lshlrev_b32_e32 v182, 16, v135
	v_pk_add_f32 v[134:135], v[38:39], v[190:191]
	v_fmac_f32_e32 v140, 0.5, v132
	v_fmac_f32_e32 v141, 0.5, v133
	v_cvt_pk_bf16_f32 v132, v140, v141
	v_fmac_f32_e32 v170, 0.5, v138
	v_fmac_f32_e32 v183, 0.5, v137
	v_and_b32_e32 v137, 0xffff0000, v132
	v_fmac_f32_e32 v142, 0.5, v134
	v_fmac_f32_e32 v171, 0.5, v139
	v_cvt_pk_bf16_f32 v134, v170, v171
	v_fmac_f32_e32 v182, 0.5, v136
	v_lshlrev_b32_e32 v136, 16, v132
	v_mul_f32_e32 v170, v137, v137
	v_fmac_f32_e32 v143, 0.5, v135
	v_cvt_pk_bf16_f32 v133, v142, v143
	v_fmac_f32_e32 v170, v136, v136
	v_lshlrev_b32_e32 v138, 16, v133
	v_and_b32_e32 v139, 0xffff0000, v133
	v_fmac_f32_e32 v170, v138, v138
	v_lshlrev_b32_e32 v140, 16, v134
	v_fmac_f32_e32 v170, v139, v139
	v_and_b32_e32 v141, 0xffff0000, v134
	v_fmac_f32_e32 v170, v140, v140
	v_cvt_pk_bf16_f32 v135, v182, v183
	v_fmac_f32_e32 v170, v141, v141
	v_lshlrev_b32_e32 v142, 16, v135
	v_and_b32_e32 v143, 0xffff0000, v135
	v_fmac_f32_e32 v170, v142, v142
	v_lshlrev_b32_e32 v136, 16, v128
	v_lshlrev_b32_e32 v171, 16, v130
	v_and_b32_e32 v182, 0xffff0000, v130
	v_lshlrev_b32_e32 v183, 16, v131
	v_and_b32_e32 v184, 0xffff0000, v131
	v_pk_add_f32 v[130:131], v[4:5], v[178:179]
	v_fmac_f32_e32 v170, v143, v143
	v_and_b32_e32 v137, 0xffff0000, v128
	v_lshlrev_b32_e32 v142, 16, v129
	v_and_b32_e32 v143, 0xffff0000, v129
	v_pk_add_f32 v[128:129], v[6:7], v[180:181]
	v_fmac_f32_e32 v136, 0.5, v130
	v_fmac_f32_e32 v137, 0.5, v131
	v_cvt_pk_bf16_f32 v136, v136, v137
	v_fmac_f32_e32 v142, 0.5, v128
	v_lshlrev_b32_e32 v128, 16, v136
	v_fmac_f32_e32 v143, 0.5, v129
	v_and_b32_e32 v129, 0xffff0000, v136
	v_fmac_f32_e32 v170, v128, v128
	v_cvt_pk_bf16_f32 v137, v142, v143
	v_fmac_f32_e32 v170, v129, v129
	v_lshlrev_b32_e32 v130, 16, v137
	v_pk_add_f32 v[140:141], v[2:3], v[176:177]
	v_pk_add_f32 v[138:139], v[0:1], v[172:173]
	v_and_b32_e32 v131, 0xffff0000, v137
	v_fmac_f32_e32 v170, v130, v130
	v_fmac_f32_e32 v171, 0.5, v138
	v_fmac_f32_e32 v182, 0.5, v139
	v_cvt_pk_bf16_f32 v138, v171, v182
	v_fmac_f32_e32 v183, 0.5, v140
	v_lshlrev_b32_e32 v140, 16, v138
	v_fmac_f32_e32 v170, v131, v131
	v_fmac_f32_e32 v184, 0.5, v141
	v_and_b32_e32 v141, 0xffff0000, v138
	v_fmac_f32_e32 v170, v140, v140
	v_cvt_pk_bf16_f32 v139, v183, v184
	v_fmac_f32_e32 v170, v141, v141
	v_lshlrev_b32_e32 v142, 16, v139
	v_and_b32_e32 v143, 0xffff0000, v139
	v_fmac_f32_e32 v170, v142, v142
	v_fmac_f32_e32 v170, v143, v143
	ds_bpermute_b32 v128, v237, v170
	v_lshl_add_u64 v[130:131], s[28:29], 0, v[174:175]
	v_lshl_add_u64 v[130:131], v[168:169], 1, v[130:131]
	global_store_dwordx4 v[130:131], v[132:135], off
	global_store_dwordx4 v[130:131], v[136:139], off offset:256
	s_waitcnt lgkmcnt(0)
	v_add_f32_e32 v128, v170, v128
	ds_bpermute_b32 v129, v238, v128
	s_and_saveexec_b64 s[12:13], s[8:9]
	s_cbranch_execz .LBB0_427
	s_waitcnt lgkmcnt(0)
	v_add_f32_e32 v130, v128, v129
	v_lshl_add_u64 v[128:129], v[166:167], 2, s[6:7]
	global_atomic_add_f32 v[128:129], v130, off offset:704

;     __device__ __forceinline__ void operator()(const f32x4 (&acc)[2][2][4][2], const Unit& u, int wr, int wc, int fr, int fq) const {
;     ...
;                 u32x4 xin[2][2];
; #pragma unroll
;                 for (int mm = 0; mm < 2; ++mm)
; #pragma unroll
;                     for (int bj = 0; bj < 2; ++bj) xin[mm][bj] = *(const u32x4*)(X + (size_t)(row0 + ai * HALF + (mp * 2 + mm) * 16) * DM + col0 + bj * HALF);
;                 f32x4 pv[2][2][2];
; #pragma unroll
;                 for (int mm = 0; mm < 2; ++mm)
; #pragma unroll
;                     for (int bj = 0; bj < 2; ++bj)
; #pragma unroll
;                         for (int n = 0; n < 2; ++n) pv[mm][bj][n] = (f32x4){0.f, 0.f, 0.f, 0.f};
;                 if (src) {
;                     u32x4 pc[2][2];
;     ...
;                     asm volatile("global_load_dwordx4 %0, %4, off sc1\n\tglobal_load_dwordx4 %1, %5, off sc1\n\tglobal_load_dwordx4 %2, %6, off sc1\n\tglobal_load_dwordx4 %3, %7, off sc1\n\ts_waitcnt vmcnt(0)"
;                                  : "=&v"(pc[0][0]), "=&v"(pc[0][1]), "=&v"(pc[1][0]), "=&v"(pc[1][1])
;                                  : "v"(src + CI(0, 0)), "v"(src + CI(0, 1)), "v"(src + CI(1, 0)), "v"(src + CI(1, 1))
;                                  : "memory");
;     ...
; #pragma unroll
;                     for (int mm = 0; mm < 2; ++mm)
; #pragma unroll
;                         for (int bj = 0; bj < 2; ++bj) { float f[8]; unpack8(pc[mm][bj], f); pv[mm][bj][0] = (f32x4){f[0], f[1], f[2], f[3]}; pv[mm][bj][1] = (f32x4){f[4], f[5], f[6], f[7]}; }
;                 }
; #pragma unroll
;                 for (int mm = 0; mm < 2; ++mm) {
;                     const int m = mp * 2 + mm;
;                     const int row = row0 + ai * HALF + m * 16;
;                     float s = 0.f;
; #pragma unroll
;                     for (int bj = 0; bj < 2; ++bj) {
;                         u32x4* px = (u32x4*)(X + (size_t)row * DM + col0 + bj * HALF);
;                         float xo[8]; unpack8(xin[mm][bj], xo);
;                         const f32x4 a0 = acc[ai][bj][m][0] + pv[mm][bj][0], a1 = acc[ai][bj][m][1] + pv[mm][bj][1];
;                         u32x4 w;
;                         w.x = cvt_pk(xo[0] + scale * a0[0], xo[1] + scale * a0[1]); w.y = cvt_pk(xo[2] + scale * a0[2], xo[3] + scale * a0[3]);
.LBB0_1167:
	s_or_b64 exec, exec, s[16:17]
	s_waitcnt vmcnt(0)
	s_mov_b64 s[38:39], 0x40000
	v_lshl_add_u64 v[250:251], v[174:175], 0, s[38:39]
	v_lshl_add_u64 v[250:251], v[172:173], 0, v[250:251]
	global_load_dwordx4 v[80:83], v[250:251], off
	global_load_dwordx4 v[84:87], v[250:251], off offset:256
	s_mov_b64 s[38:39], 0x48000
	v_lshl_add_u64 v[252:253], v[174:175], 0, s[38:39]
	v_lshl_add_u64 v[252:253], v[172:173], 0, v[252:253]
	global_load_dwordx4 v[88:91], v[252:253], off
	global_load_dwordx4 v[92:95], v[252:253], off offset:256
	s_and_saveexec_b64 s[16:17], vcc
	s_mov_b64 s[38:39], 0x2000
	v_lshl_add_u64 v[250:251], v[170:171], 0, s[38:39]
	global_load_dwordx4 v[112:115], v[250:251], off sc1
	s_mov_b64 s[38:39], 0x3000
	v_lshl_add_u64 v[252:253], v[170:171], 0, s[38:39]
	global_load_dwordx4 v[116:119], v[252:253], off sc1
	s_mov_b64 s[38:39], 0x2400
	v_lshl_add_u64 v[250:251], v[170:171], 0, s[38:39]
	global_load_dwordx4 v[120:123], v[250:251], off sc1
	s_mov_b64 s[38:39], 0x3400
	v_lshl_add_u64 v[252:253], v[170:171], 0, s[38:39]
	global_load_dwordx4 v[124:127], v[252:253], off sc1
	s_or_b64 exec, exec, s[16:17]
	v_lshlrev_b32_e32 v214, 16, v140
	v_and_b32_e32 v215, 0xffff0000, v140
	v_lshlrev_b32_e32 v244, 16, v141
	v_and_b32_e32 v245, 0xffff0000, v141
	v_pk_add_f32 v[140:141], v[108:109], v[208:209]
	v_lshlrev_b32_e32 v246, 16, v142
	v_and_b32_e32 v247, 0xffff0000, v142
	v_lshlrev_b32_e32 v248, 16, v143
	v_and_b32_e32 v249, 0xffff0000, v143
	v_pk_add_f32 v[142:143], v[110:111], v[210:211]
	v_add_f32_e32 v140, v140, v214
	v_add_f32_e32 v141, v141, v215
	v_pk_add_f32 v[204:205], v[104:105], v[204:205]
	v_cvt_pk_bf16_f32 v140, v140, v141
	v_add_f32_e32 v141, v142, v244
	v_add_f32_e32 v142, v143, v245
	v_pk_add_f32 v[206:207], v[106:107], v[206:207]
	v_cvt_pk_bf16_f32 v141, v141, v142
	v_add_f32_e32 v142, v204, v246
	v_add_f32_e32 v143, v205, v247
	v_cvt_pk_bf16_f32 v142, v142, v143
	v_add_f32_e32 v143, v206, v248
	v_add_f32_e32 v204, v207, v249
	v_and_b32_e32 v205, 0xffff0000, v140
	v_cvt_pk_bf16_f32 v143, v143, v204
	v_lshlrev_b32_e32 v204, 16, v140
	v_mul_f32_e32 v205, v205, v205
	v_lshlrev_b32_e32 v206, 16, v141
	v_fmac_f32_e32 v205, v204, v204
	v_and_b32_e32 v207, 0xffff0000, v141
	v_fmac_f32_e32 v205, v206, v206
	v_lshlrev_b32_e32 v208, 16, v142
	v_fmac_f32_e32 v205, v207, v207
	v_and_b32_e32 v209, 0xffff0000, v142
	v_fmac_f32_e32 v205, v208, v208
	v_lshlrev_b32_e32 v210, 16, v143
	v_fmac_f32_e32 v205, v209, v209
	v_and_b32_e32 v211, 0xffff0000, v143
	v_fmac_f32_e32 v205, v210, v210
	v_lshlrev_b32_e32 v204, 16, v136
	v_and_b32_e32 v206, 0xffff0000, v136
	v_lshlrev_b32_e32 v207, 16, v137
	v_and_b32_e32 v208, 0xffff0000, v137
	v_pk_add_f32 v[136:137], v[78:79], v[202:203]
	v_fmac_f32_e32 v205, v211, v211
	v_lshlrev_b32_e32 v209, 16, v138
	v_and_b32_e32 v210, 0xffff0000, v138
	v_lshlrev_b32_e32 v211, 16, v139
	v_and_b32_e32 v214, 0xffff0000, v139
	v_pk_add_f32 v[138:139], v[76:77], v[200:201]
	v_pk_add_f32 v[200:201], v[74:75], v[198:199]
	v_pk_add_f32 v[198:199], v[72:73], v[196:197]
	v_add_f32_e32 v136, v136, v207
	v_add_f32_e32 v137, v137, v208
	v_cvt_pk_bf16_f32 v197, v136, v137
	v_add_f32_e32 v136, v198, v209
	v_add_f32_e32 v137, v199, v210
	v_cvt_pk_bf16_f32 v198, v136, v137
	v_add_f32_e32 v136, v200, v211
	v_add_f32_e32 v138, v138, v204
	v_add_f32_e32 v139, v139, v206
	v_cvt_pk_bf16_f32 v196, v138, v139
	v_add_f32_e32 v137, v201, v214
	v_cvt_pk_bf16_f32 v199, v136, v137
	v_lshlrev_b32_e32 v136, 16, v196
	v_and_b32_e32 v137, 0xffff0000, v196
	v_fmac_f32_e32 v205, v136, v136
	v_lshlrev_b32_e32 v138, 16, v197
	v_fmac_f32_e32 v205, v137, v137
	v_and_b32_e32 v139, 0xffff0000, v197
	v_fmac_f32_e32 v205, v138, v138
	v_lshlrev_b32_e32 v200, 16, v198
	v_fmac_f32_e32 v205, v139, v139
	v_and_b32_e32 v201, 0xffff0000, v198
	v_fmac_f32_e32 v205, v200, v200
	v_lshlrev_b32_e32 v202, 16, v199
	v_fmac_f32_e32 v205, v201, v201
	v_and_b32_e32 v203, 0xffff0000, v199
	v_fmac_f32_e32 v205, v202, v202
	v_fmac_f32_e32 v205, v203, v203
	ds_bpermute_b32 v136, v237, v205
	v_lshl_add_u64 v[138:139], s[36:37], 0, v[186:187]
	v_lshl_add_u64 v[138:139], v[168:169], 1, v[138:139]
	global_store_dwordx4 v[138:139], v[140:143], off
	global_store_dwordx4 v[138:139], v[196:199], off offset:256
	s_waitcnt lgkmcnt(0)
	v_add_f32_e32 v136, v205, v136
	ds_bpermute_b32 v137, v238, v136
	s_and_saveexec_b64 s[16:17], s[12:13]
	s_cbranch_execz .LBB0_1169
	s_waitcnt lgkmcnt(0)
	v_add_f32_e32 v138, v136, v137
	v_lshl_add_u64 v[136:137], v[166:167], 2, s[4:5]
	global_atomic_add_f32 v[136:137], v138, off offset:128
;     __device__ __forceinline__ void operator()(const f32x4 (&acc)[2][2][4][2], const Unit& u, int wr, int wc, int fr, int fq) const {
;     ...
;                 u32x4 xin[2][2];
; #pragma unroll
;                 for (int mm = 0; mm < 2; ++mm)
; #pragma unroll
;                     for (int bj = 0; bj < 2; ++bj) xin[mm][bj] = *(const u32x4*)(X + (size_t)(row0 + ai * HALF + (mp * 2 + mm) * 16) * DM + col0 + bj * HALF);
;                 f32x4 pv[2][2][2];
; #pragma unroll
;                 for (int mm = 0; mm < 2; ++mm)
; #pragma unroll
;                     for (int bj = 0; bj < 2; ++bj)
; #pragma unroll
;                         for (int n = 0; n < 2; ++n) pv[mm][bj][n] = (f32x4){0.f, 0.f, 0.f, 0.f};
;                 if (src) {
;                     u32x4 pc[2][2];
;     ...
;                     asm volatile("global_load_dwordx4 %0, %4, off sc1\n\tglobal_load_dwordx4 %1, %5, off sc1\n\tglobal_load_dwordx4 %2, %6, off sc1\n\tglobal_load_dwordx4 %3, %7, off sc1\n\ts_waitcnt vmcnt(0)"
;                                  : "=&v"(pc[0][0]), "=&v"(pc[0][1]), "=&v"(pc[1][0]), "=&v"(pc[1][1])
;                                  : "v"(src + CI(0, 0)), "v"(src + CI(0, 1)), "v"(src + CI(1, 0)), "v"(src + CI(1, 1))
;                                  : "memory");
;     ...
; #pragma unroll
;                     for (int mm = 0; mm < 2; ++mm)
; #pragma unroll
;                         for (int bj = 0; bj < 2; ++bj) { float f[8]; unpack8(pc[mm][bj], f); pv[mm][bj][0] = (f32x4){f[0], f[1], f[2], f[3]}; pv[mm][bj][1] = (f32x4){f[4], f[5], f[6], f[7]}; }
;                 }
; #pragma unroll
;                 for (int mm = 0; mm < 2; ++mm) {
;                     const int m = mp * 2 + mm;
;                     const int row = row0 + ai * HALF + m * 16;
;                     float s = 0.f;
; #pragma unroll
;                     for (int bj = 0; bj < 2; ++bj) {
;                         u32x4* px = (u32x4*)(X + (size_t)row * DM + col0 + bj * HALF);
;                         float xo[8]; unpack8(xin[mm][bj], xo);
;                         const f32x4 a0 = acc[ai][bj][m][0] + pv[mm][bj][0], a1 = acc[ai][bj][m][1] + pv[mm][bj][1];
;                         u32x4 w;
;                         w.x = cvt_pk(xo[0] + scale * a0[0], xo[1] + scale * a0[1]); w.y = cvt_pk(xo[2] + scale * a0[2], xo[3] + scale * a0[3]);
.LBB0_1169:
	s_or_b64 exec, exec, s[16:17]
	v_lshlrev_b32_e32 v140, 16, v132
	v_and_b32_e32 v141, 0xffff0000, v132
	v_lshlrev_b32_e32 v142, 16, v133
	v_and_b32_e32 v143, 0xffff0000, v133
	v_pk_add_f32 v[132:133], v[100:101], v[192:193]
	v_lshlrev_b32_e32 v186, 16, v134
	v_and_b32_e32 v187, 0xffff0000, v134
	v_lshlrev_b32_e32 v196, 16, v135
	v_and_b32_e32 v197, 0xffff0000, v135
	v_pk_add_f32 v[134:135], v[102:103], v[194:195]
	v_add_f32_e32 v132, v132, v140
	v_add_f32_e32 v133, v133, v141
	v_pk_add_f32 v[138:139], v[96:97], v[188:189]
	v_cvt_pk_bf16_f32 v132, v132, v133
	v_add_f32_e32 v133, v134, v142
	v_add_f32_e32 v134, v135, v143
	s_waitcnt lgkmcnt(0)
	v_pk_add_f32 v[136:137], v[98:99], v[190:191]
	v_cvt_pk_bf16_f32 v133, v133, v134
	v_add_f32_e32 v134, v138, v186
	v_add_f32_e32 v135, v139, v187
	v_cvt_pk_bf16_f32 v134, v134, v135
	v_add_f32_e32 v135, v136, v196
	v_add_f32_e32 v136, v137, v197
	v_and_b32_e32 v137, 0xffff0000, v132
	v_cvt_pk_bf16_f32 v135, v135, v136
	v_lshlrev_b32_e32 v136, 16, v132
	v_mul_f32_e32 v186, v137, v137
	v_lshlrev_b32_e32 v138, 16, v133
	v_fmac_f32_e32 v186, v136, v136
	v_and_b32_e32 v139, 0xffff0000, v133
	v_fmac_f32_e32 v186, v138, v138
	v_lshlrev_b32_e32 v140, 16, v134
	v_fmac_f32_e32 v186, v139, v139
	v_and_b32_e32 v141, 0xffff0000, v134
	v_fmac_f32_e32 v186, v140, v140
	v_lshlrev_b32_e32 v142, 16, v135
	v_fmac_f32_e32 v186, v141, v141
	v_and_b32_e32 v143, 0xffff0000, v135
	v_fmac_f32_e32 v186, v142, v142
	v_fmac_f32_e32 v186, v143, v143
	v_lshlrev_b32_e32 v136, 16, v128
	v_and_b32_e32 v137, 0xffff0000, v128
	v_lshlrev_b32_e32 v142, 16, v129
	v_and_b32_e32 v143, 0xffff0000, v129
	v_pk_add_f32 v[128:129], v[70:71], v[184:185]
	v_lshlrev_b32_e32 v187, 16, v130
	v_and_b32_e32 v188, 0xffff0000, v130
	v_lshlrev_b32_e32 v189, 16, v131
	v_and_b32_e32 v190, 0xffff0000, v131
	v_pk_add_f32 v[130:131], v[68:69], v[182:183]
	v_pk_add_f32 v[138:139], v[64:65], v[178:179]
	v_add_f32_e32 v128, v128, v142
	v_pk_add_f32 v[140:141], v[66:67], v[180:181]
	v_add_f32_e32 v131, v131, v137
	v_add_f32_e32 v129, v129, v143
	v_cvt_pk_bf16_f32 v137, v128, v129
	v_add_f32_e32 v128, v138, v187
	v_add_f32_e32 v129, v139, v188
	v_cvt_pk_bf16_f32 v138, v128, v129
	v_add_f32_e32 v128, v140, v189
	v_add_f32_e32 v130, v130, v136
	v_cvt_pk_bf16_f32 v136, v130, v131
	v_add_f32_e32 v129, v141, v190
	v_cvt_pk_bf16_f32 v139, v128, v129
	v_lshlrev_b32_e32 v128, 16, v136
	v_and_b32_e32 v129, 0xffff0000, v136
	v_fmac_f32_e32 v186, v128, v128
	v_lshlrev_b32_e32 v130, 16, v137
	v_fmac_f32_e32 v186, v129, v129
	v_and_b32_e32 v131, 0xffff0000, v137
	v_fmac_f32_e32 v186, v130, v130
	v_lshlrev_b32_e32 v140, 16, v138
	v_fmac_f32_e32 v186, v131, v131
	v_and_b32_e32 v141, 0xffff0000, v138
	v_fmac_f32_e32 v186, v140, v140
	v_lshlrev_b32_e32 v142, 16, v139
	v_fmac_f32_e32 v186, v141, v141
	v_and_b32_e32 v143, 0xffff0000, v139
	v_fmac_f32_e32 v186, v142, v142
	v_fmac_f32_e32 v186, v143, v143
	ds_bpermute_b32 v128, v237, v186
	v_lshl_add_u64 v[130:131], s[36:37], 0, v[176:177]
	v_lshl_add_u64 v[130:131], v[168:169], 1, v[130:131]
	global_store_dwordx4 v[130:131], v[132:135], off
	global_store_dwordx4 v[130:131], v[136:139], off offset:256
	s_waitcnt lgkmcnt(0)
	v_add_f32_e32 v128, v186, v128
	ds_bpermute_b32 v129, v238, v128
	s_and_saveexec_b64 s[16:17], s[12:13]
	s_cbranch_execz .LBB0_1171
	s_waitcnt lgkmcnt(0)
	v_add_f32_e32 v130, v128, v129
	v_lshl_add_u64 v[128:129], v[166:167], 2, s[4:5]
	global_atomic_add_f32 v[128:129], v130, off offset:192
.LBB0_1171:
	s_or_b64 exec, exec, s[16:17]
	s_waitcnt vmcnt(4)
	s_mov_b64 s[16:17], 0x40000
	v_lshl_add_u64 v[186:187], v[174:175], 0, s[16:17]
	s_mov_b64 s[16:17], 0x48000
	s_waitcnt lgkmcnt(0)
	v_lshl_add_u64 v[128:129], v[172:173], 0, v[186:187]
	v_lshl_add_u64 v[176:177], v[174:175], 0, s[16:17]
	v_lshl_add_u64 v[128:129], v[172:173], 0, v[176:177]
	s_nop 0
	v_mov_b32_e32 v140, v80
	v_mov_b32_e32 v141, v81
	v_mov_b32_e32 v142, v82
	v_mov_b32_e32 v143, v83
	v_mov_b32_e32 v136, v84
	v_mov_b32_e32 v137, v85
	v_mov_b32_e32 v138, v86
	v_mov_b32_e32 v139, v87
	v_mov_b32_e32 v132, v88
	v_mov_b32_e32 v133, v89
	v_mov_b32_e32 v134, v90
	v_mov_b32_e32 v135, v91
	v_mov_b32_e32 v128, v92
	v_mov_b32_e32 v129, v93
	v_mov_b32_e32 v130, v94
	v_mov_b32_e32 v131, v95
	v_mov_b32_e32 v178, 0
	v_mov_b32_e32 v179, 0
	v_mov_b32_e32 v180, 0
	v_mov_b32_e32 v181, 0
	v_mov_b32_e32 v182, 0
	v_mov_b32_e32 v183, 0
	v_mov_b32_e32 v184, 0
	v_mov_b32_e32 v185, 0
	v_mov_b32_e32 v188, 0
	v_mov_b32_e32 v189, 0
	v_mov_b32_e32 v190, 0
	v_mov_b32_e32 v191, 0
	v_mov_b32_e32 v192, 0
	v_mov_b32_e32 v193, 0
	v_mov_b32_e32 v194, 0
	v_mov_b32_e32 v195, 0
	v_mov_b32_e32 v196, 0
	v_mov_b32_e32 v197, 0
	v_mov_b32_e32 v198, 0
	v_mov_b32_e32 v199, 0
	v_mov_b32_e32 v200, 0
	v_mov_b32_e32 v201, 0
	v_mov_b32_e32 v202, 0
	v_mov_b32_e32 v203, 0
	v_mov_b32_e32 v204, 0
	v_mov_b32_e32 v205, 0
	v_mov_b32_e32 v206, 0
	v_mov_b32_e32 v207, 0
	v_mov_b32_e32 v208, 0
	v_mov_b32_e32 v209, 0
	v_mov_b32_e32 v210, 0
	v_mov_b32_e32 v211, 0
	s_and_saveexec_b64 s[16:17], vcc
	s_cbranch_execz .LBB0_1173
	s_mov_b64 s[38:39], 0x2000
	v_lshl_add_u64 v[192:193], v[170:171], 0, s[38:39]
	s_mov_b64 s[38:39], 0x3000
	v_lshl_add_u64 v[194:195], v[170:171], 0, s[38:39]
	s_mov_b64 s[38:39], 0x2400
	v_lshl_add_u64 v[196:197], v[170:171], 0, s[38:39]
	s_mov_b64 s[38:39], 0x3400
	v_lshl_add_u64 v[198:199], v[170:171], 0, s[38:39]
	v_mov_b32_e32 v178, v112
	v_mov_b32_e32 v179, v113
	v_mov_b32_e32 v180, v114
	v_mov_b32_e32 v181, v115
	v_mov_b32_e32 v182, v116
	v_mov_b32_e32 v183, v117
	v_mov_b32_e32 v184, v118
	v_mov_b32_e32 v185, v119
	v_mov_b32_e32 v188, v120
	v_mov_b32_e32 v189, v121
	v_mov_b32_e32 v190, v122
	v_mov_b32_e32 v191, v123
	v_mov_b32_e32 v244, v124
	v_mov_b32_e32 v245, v125
	v_mov_b32_e32 v246, v126
	v_mov_b32_e32 v247, v127
	s_nop 0
	v_lshlrev_b32_e32 v208, 16, v178
	v_and_b32_e32 v209, 0xffff0000, v178
	v_lshlrev_b32_e32 v210, 16, v179
	v_and_b32_e32 v211, 0xffff0000, v179
	v_lshlrev_b32_e32 v204, 16, v180
	v_and_b32_e32 v205, 0xffff0000, v180
	v_lshlrev_b32_e32 v206, 16, v181
	v_and_b32_e32 v207, 0xffff0000, v181
	v_lshlrev_b32_e32 v200, 16, v182
	v_and_b32_e32 v201, 0xffff0000, v182
	v_lshlrev_b32_e32 v202, 16, v183
	v_and_b32_e32 v203, 0xffff0000, v183
	v_lshlrev_b32_e32 v196, 16, v184
	v_and_b32_e32 v197, 0xffff0000, v184
	v_lshlrev_b32_e32 v198, 16, v185
	v_and_b32_e32 v199, 0xffff0000, v185
	v_lshlrev_b32_e32 v192, 16, v188
	v_and_b32_e32 v193, 0xffff0000, v188
	v_lshlrev_b32_e32 v194, 16, v189
	v_and_b32_e32 v195, 0xffff0000, v189
	v_lshlrev_b32_e32 v188, 16, v190
	v_and_b32_e32 v189, 0xffff0000, v190
	v_lshlrev_b32_e32 v190, 16, v191
	v_and_b32_e32 v191, 0xffff0000, v191
	v_lshlrev_b32_e32 v182, 16, v244
	v_and_b32_e32 v183, 0xffff0000, v244
	v_lshlrev_b32_e32 v184, 16, v245
	v_and_b32_e32 v185, 0xffff0000, v245
	v_lshlrev_b32_e32 v178, 16, v246
	v_and_b32_e32 v179, 0xffff0000, v246
	v_lshlrev_b32_e32 v180, 16, v247
	v_and_b32_e32 v181, 0xffff0000, v247
;     __device__ __forceinline__ void operator()(const f32x4 (&acc)[2][2][4][2], const Unit& u, int wr, int wc, int fr, int fq) const {
;     ...
;                 u32x4 xin[2][2];
; #pragma unroll
;                 for (int mm = 0; mm < 2; ++mm)
; #pragma unroll
;                     for (int bj = 0; bj < 2; ++bj) xin[mm][bj] = *(const u32x4*)(X + (size_t)(row0 + ai * HALF + (mp * 2 + mm) * 16) * DM + col0 + bj * HALF);
;                 f32x4 pv[2][2][2];
; #pragma unroll
;                 for (int mm = 0; mm < 2; ++mm)
; #pragma unroll
;                     for (int bj = 0; bj < 2; ++bj)
; #pragma unroll
;                         for (int n = 0; n < 2; ++n) pv[mm][bj][n] = (f32x4){0.f, 0.f, 0.f, 0.f};
;                 if (src) {
;                     u32x4 pc[2][2];
;     ...
;                     asm volatile("global_load_dwordx4 %0, %4, off sc1\n\tglobal_load_dwordx4 %1, %5, off sc1\n\tglobal_load_dwordx4 %2, %6, off sc1\n\tglobal_load_dwordx4 %3, %7, off sc1\n\ts_waitcnt vmcnt(0)"
;                                  : "=&v"(pc[0][0]), "=&v"(pc[0][1]), "=&v"(pc[1][0]), "=&v"(pc[1][1])
;                                  : "v"(src + CI(0, 0)), "v"(src + CI(0, 1)), "v"(src + CI(1, 0)), "v"(src + CI(1, 1))
;                                  : "memory");
;     ...
; #pragma unroll
;                     for (int mm = 0; mm < 2; ++mm)
; #pragma unroll
;                         for (int bj = 0; bj < 2; ++bj) { float f[8]; unpack8(pc[mm][bj], f); pv[mm][bj][0] = (f32x4){f[0], f[1], f[2], f[3]}; pv[mm][bj][1] = (f32x4){f[4], f[5], f[6], f[7]}; }
;                 }
; #pragma unroll
;                 for (int mm = 0; mm < 2; ++mm) {
;                     const int m = mp * 2 + mm;
;                     const int row = row0 + ai * HALF + m * 16;
;                     float s = 0.f;
; #pragma unroll
;                     for (int bj = 0; bj < 2; ++bj) {
;                         u32x4* px = (u32x4*)(X + (size_t)row * DM + col0 + bj * HALF);
;                         float xo[8]; unpack8(xin[mm][bj], xo);
;                         const f32x4 a0 = acc[ai][bj][m][0] + pv[mm][bj][0], a1 = acc[ai][bj][m][1] + pv[mm][bj][1];
;                         u32x4 w;
;                         w.x = cvt_pk(xo[0] + scale * a0[0], xo[1] + scale * a0[1]); w.y = cvt_pk(xo[2] + scale * a0[2], xo[3] + scale * a0[3]);
.LBB0_1173:
	s_or_b64 exec, exec, s[16:17]
	s_mov_b64 s[38:39], 0x50000
	v_lshl_add_u64 v[250:251], v[174:175], 0, s[38:39]
	v_lshl_add_u64 v[250:251], v[172:173], 0, v[250:251]
	global_load_dwordx4 v[64:67], v[250:251], off
	global_load_dwordx4 v[68:71], v[250:251], off offset:256
	s_mov_b64 s[38:39], 0x58000
	v_lshl_add_u64 v[252:253], v[174:175], 0, s[38:39]
	v_lshl_add_u64 v[252:253], v[172:173], 0, v[252:253]
	global_load_dwordx4 v[72:75], v[252:253], off
	global_load_dwordx4 v[76:79], v[252:253], off offset:256
	s_and_saveexec_b64 s[16:17], vcc
	s_mov_b64 s[38:39], 0x2800
	v_lshl_add_u64 v[250:251], v[170:171], 0, s[38:39]
	global_load_dwordx4 v[96:99], v[250:251], off sc1
	s_mov_b64 s[38:39], 0x3800
	v_lshl_add_u64 v[252:253], v[170:171], 0, s[38:39]
	global_load_dwordx4 v[100:103], v[252:253], off sc1
	s_mov_b64 s[38:39], 0x2c00
	v_lshl_add_u64 v[250:251], v[170:171], 0, s[38:39]
	global_load_dwordx4 v[104:107], v[250:251], off sc1
	s_mov_b64 s[38:39], 0x3c00
	v_lshl_add_u64 v[252:253], v[170:171], 0, s[38:39]
	global_load_dwordx4 v[108:111], v[252:253], off sc1
	s_or_b64 exec, exec, s[16:17]
	v_lshlrev_b32_e32 v214, 16, v140
	v_and_b32_e32 v215, 0xffff0000, v140
	v_lshlrev_b32_e32 v244, 16, v141
	v_and_b32_e32 v245, 0xffff0000, v141
	v_pk_add_f32 v[140:141], v[60:61], v[208:209]
	v_lshlrev_b32_e32 v246, 16, v142
	v_and_b32_e32 v247, 0xffff0000, v142
	v_lshlrev_b32_e32 v248, 16, v143
	v_and_b32_e32 v249, 0xffff0000, v143
	v_pk_add_f32 v[142:143], v[62:63], v[210:211]
	v_add_f32_e32 v140, v140, v214
	v_add_f32_e32 v141, v141, v215
	v_pk_add_f32 v[204:205], v[56:57], v[204:205]
	v_cvt_pk_bf16_f32 v140, v140, v141
	v_add_f32_e32 v141, v142, v244
	v_add_f32_e32 v142, v143, v245
	v_pk_add_f32 v[206:207], v[58:59], v[206:207]
	v_cvt_pk_bf16_f32 v141, v141, v142
	v_add_f32_e32 v142, v204, v246
	v_add_f32_e32 v143, v205, v247
	v_cvt_pk_bf16_f32 v142, v142, v143
	v_add_f32_e32 v143, v206, v248
	v_add_f32_e32 v204, v207, v249
	v_and_b32_e32 v205, 0xffff0000, v140
	v_cvt_pk_bf16_f32 v143, v143, v204
	v_lshlrev_b32_e32 v204, 16, v140
	v_mul_f32_e32 v205, v205, v205
	v_lshlrev_b32_e32 v206, 16, v141
	v_fmac_f32_e32 v205, v204, v204
	v_and_b32_e32 v207, 0xffff0000, v141
	v_fmac_f32_e32 v205, v206, v206
	v_lshlrev_b32_e32 v208, 16, v142
	v_fmac_f32_e32 v205, v207, v207
	v_and_b32_e32 v209, 0xffff0000, v142
	v_fmac_f32_e32 v205, v208, v208
	v_lshlrev_b32_e32 v210, 16, v143
	v_fmac_f32_e32 v205, v209, v209
	v_and_b32_e32 v211, 0xffff0000, v143
	v_fmac_f32_e32 v205, v210, v210
	v_lshlrev_b32_e32 v204, 16, v136
	v_and_b32_e32 v206, 0xffff0000, v136
	v_lshlrev_b32_e32 v207, 16, v137
	v_and_b32_e32 v208, 0xffff0000, v137
	v_pk_add_f32 v[136:137], v[30:31], v[202:203]
	v_fmac_f32_e32 v205, v211, v211
	v_lshlrev_b32_e32 v209, 16, v138
	v_and_b32_e32 v210, 0xffff0000, v138
	v_lshlrev_b32_e32 v211, 16, v139
	v_and_b32_e32 v214, 0xffff0000, v139
	v_pk_add_f32 v[138:139], v[28:29], v[200:201]
	v_pk_add_f32 v[200:201], v[26:27], v[198:199]
	v_pk_add_f32 v[198:199], v[24:25], v[196:197]
	v_add_f32_e32 v136, v136, v207
	v_add_f32_e32 v137, v137, v208
	v_cvt_pk_bf16_f32 v197, v136, v137
	v_add_f32_e32 v136, v198, v209
	v_add_f32_e32 v137, v199, v210
	v_cvt_pk_bf16_f32 v198, v136, v137
	v_add_f32_e32 v136, v200, v211
	v_add_f32_e32 v138, v138, v204
	v_add_f32_e32 v139, v139, v206
	v_cvt_pk_bf16_f32 v196, v138, v139
	v_add_f32_e32 v137, v201, v214
	v_cvt_pk_bf16_f32 v199, v136, v137
	v_lshlrev_b32_e32 v136, 16, v196
	v_and_b32_e32 v137, 0xffff0000, v196
	v_fmac_f32_e32 v205, v136, v136
	v_lshlrev_b32_e32 v138, 16, v197
	v_fmac_f32_e32 v205, v137, v137
	v_and_b32_e32 v139, 0xffff0000, v197
	v_fmac_f32_e32 v205, v138, v138
	v_lshlrev_b32_e32 v200, 16, v198
	v_fmac_f32_e32 v205, v139, v139
	v_and_b32_e32 v201, 0xffff0000, v198
	v_fmac_f32_e32 v205, v200, v200
	v_lshlrev_b32_e32 v202, 16, v199
	v_fmac_f32_e32 v205, v201, v201
	v_and_b32_e32 v203, 0xffff0000, v199
	v_fmac_f32_e32 v205, v202, v202
	v_fmac_f32_e32 v205, v203, v203
	ds_bpermute_b32 v136, v237, v205
	v_lshl_add_u64 v[138:139], s[36:37], 0, v[186:187]
	v_lshl_add_u64 v[138:139], v[168:169], 1, v[138:139]
	global_store_dwordx4 v[138:139], v[140:143], off
	global_store_dwordx4 v[138:139], v[196:199], off offset:256
	s_waitcnt lgkmcnt(0)
	v_add_f32_e32 v136, v205, v136
	ds_bpermute_b32 v137, v238, v136
	s_and_saveexec_b64 s[16:17], s[12:13]
	s_cbranch_execz .LBB0_1175
	s_waitcnt lgkmcnt(0)
	v_add_f32_e32 v138, v136, v137
	v_lshl_add_u64 v[136:137], v[166:167], 2, s[4:5]
	global_atomic_add_f32 v[136:137], v138, off offset:512
;     __device__ __forceinline__ void operator()(const f32x4 (&acc)[2][2][4][2], const Unit& u, int wr, int wc, int fr, int fq) const {
;     ...
;                 u32x4 xin[2][2];
; #pragma unroll
;                 for (int mm = 0; mm < 2; ++mm)
; #pragma unroll
;                     for (int bj = 0; bj < 2; ++bj) xin[mm][bj] = *(const u32x4*)(X + (size_t)(row0 + ai * HALF + (mp * 2 + mm) * 16) * DM + col0 + bj * HALF);
;                 f32x4 pv[2][2][2];
; #pragma unroll
;                 for (int mm = 0; mm < 2; ++mm)
; #pragma unroll
;                     for (int bj = 0; bj < 2; ++bj)
; #pragma unroll
;                         for (int n = 0; n < 2; ++n) pv[mm][bj][n] = (f32x4){0.f, 0.f, 0.f, 0.f};
;                 if (src) {
;                     u32x4 pc[2][2];
;     ...
;                     asm volatile("global_load_dwordx4 %0, %4, off sc1\n\tglobal_load_dwordx4 %1, %5, off sc1\n\tglobal_load_dwordx4 %2, %6, off sc1\n\tglobal_load_dwordx4 %3, %7, off sc1\n\ts_waitcnt vmcnt(0)"
;                                  : "=&v"(pc[0][0]), "=&v"(pc[0][1]), "=&v"(pc[1][0]), "=&v"(pc[1][1])
;                                  : "v"(src + CI(0, 0)), "v"(src + CI(0, 1)), "v"(src + CI(1, 0)), "v"(src + CI(1, 1))
;                                  : "memory");
;     ...
; #pragma unroll
;                     for (int mm = 0; mm < 2; ++mm)
; #pragma unroll
;                         for (int bj = 0; bj < 2; ++bj) { float f[8]; unpack8(pc[mm][bj], f); pv[mm][bj][0] = (f32x4){f[0], f[1], f[2], f[3]}; pv[mm][bj][1] = (f32x4){f[4], f[5], f[6], f[7]}; }
;                 }
; #pragma unroll
;                 for (int mm = 0; mm < 2; ++mm) {
;                     const int m = mp * 2 + mm;
;                     const int row = row0 + ai * HALF + m * 16;
;                     float s = 0.f;
; #pragma unroll
;                     for (int bj = 0; bj < 2; ++bj) {
;                         u32x4* px = (u32x4*)(X + (size_t)row * DM + col0 + bj * HALF);
;                         float xo[8]; unpack8(xin[mm][bj], xo);
;                         const f32x4 a0 = acc[ai][bj][m][0] + pv[mm][bj][0], a1 = acc[ai][bj][m][1] + pv[mm][bj][1];
;                         u32x4 w;
;                         w.x = cvt_pk(xo[0] + scale * a0[0], xo[1] + scale * a0[1]); w.y = cvt_pk(xo[2] + scale * a0[2], xo[3] + scale * a0[3]);
.LBB0_1175:
	s_or_b64 exec, exec, s[16:17]
	v_lshlrev_b32_e32 v140, 16, v132
	v_and_b32_e32 v141, 0xffff0000, v132
	v_lshlrev_b32_e32 v142, 16, v133
	v_and_b32_e32 v143, 0xffff0000, v133
	v_pk_add_f32 v[132:133], v[52:53], v[192:193]
	v_lshlrev_b32_e32 v186, 16, v134
	v_and_b32_e32 v187, 0xffff0000, v134
	v_lshlrev_b32_e32 v196, 16, v135
	v_and_b32_e32 v197, 0xffff0000, v135
	v_pk_add_f32 v[134:135], v[54:55], v[194:195]
	v_add_f32_e32 v132, v132, v140
	v_add_f32_e32 v133, v133, v141
	v_pk_add_f32 v[138:139], v[48:49], v[188:189]
	v_cvt_pk_bf16_f32 v132, v132, v133
	v_add_f32_e32 v133, v134, v142
	v_add_f32_e32 v134, v135, v143
	s_waitcnt lgkmcnt(0)
	v_pk_add_f32 v[136:137], v[50:51], v[190:191]
	v_cvt_pk_bf16_f32 v133, v133, v134
	v_add_f32_e32 v134, v138, v186
	v_add_f32_e32 v135, v139, v187
	v_cvt_pk_bf16_f32 v134, v134, v135
	v_add_f32_e32 v135, v136, v196
	v_add_f32_e32 v136, v137, v197
	v_and_b32_e32 v137, 0xffff0000, v132
	v_cvt_pk_bf16_f32 v135, v135, v136
	v_lshlrev_b32_e32 v136, 16, v132
	v_mul_f32_e32 v186, v137, v137
	v_lshlrev_b32_e32 v138, 16, v133
	v_fmac_f32_e32 v186, v136, v136
	v_and_b32_e32 v139, 0xffff0000, v133
	v_fmac_f32_e32 v186, v138, v138
	v_lshlrev_b32_e32 v140, 16, v134
	v_fmac_f32_e32 v186, v139, v139
	v_and_b32_e32 v141, 0xffff0000, v134
	v_fmac_f32_e32 v186, v140, v140
	v_lshlrev_b32_e32 v142, 16, v135
	v_fmac_f32_e32 v186, v141, v141
	v_and_b32_e32 v143, 0xffff0000, v135
	v_fmac_f32_e32 v186, v142, v142
	v_fmac_f32_e32 v186, v143, v143
	v_lshlrev_b32_e32 v136, 16, v128
	v_and_b32_e32 v137, 0xffff0000, v128
	v_lshlrev_b32_e32 v142, 16, v129
	v_and_b32_e32 v143, 0xffff0000, v129
	v_pk_add_f32 v[128:129], v[22:23], v[184:185]
	v_lshlrev_b32_e32 v187, 16, v130
	v_and_b32_e32 v188, 0xffff0000, v130
	v_lshlrev_b32_e32 v189, 16, v131
	v_and_b32_e32 v190, 0xffff0000, v131
	v_pk_add_f32 v[130:131], v[20:21], v[182:183]
	v_pk_add_f32 v[138:139], v[16:17], v[178:179]
	v_add_f32_e32 v128, v128, v142
	v_pk_add_f32 v[140:141], v[18:19], v[180:181]
	v_add_f32_e32 v131, v131, v137
	v_add_f32_e32 v129, v129, v143
	v_cvt_pk_bf16_f32 v137, v128, v129
	v_add_f32_e32 v128, v138, v187
	v_add_f32_e32 v129, v139, v188
	v_cvt_pk_bf16_f32 v138, v128, v129
	v_add_f32_e32 v128, v140, v189
	v_add_f32_e32 v130, v130, v136
	v_cvt_pk_bf16_f32 v136, v130, v131
	v_add_f32_e32 v129, v141, v190
	v_cvt_pk_bf16_f32 v139, v128, v129
	v_lshlrev_b32_e32 v128, 16, v136
	v_and_b32_e32 v129, 0xffff0000, v136
	v_fmac_f32_e32 v186, v128, v128
	v_lshlrev_b32_e32 v130, 16, v137
	v_fmac_f32_e32 v186, v129, v129
	v_and_b32_e32 v131, 0xffff0000, v137
	v_fmac_f32_e32 v186, v130, v130
	v_lshlrev_b32_e32 v140, 16, v138
	v_fmac_f32_e32 v186, v131, v131
	v_and_b32_e32 v141, 0xffff0000, v138
	v_fmac_f32_e32 v186, v140, v140
	v_lshlrev_b32_e32 v142, 16, v139
	v_fmac_f32_e32 v186, v141, v141
	v_and_b32_e32 v143, 0xffff0000, v139
	v_fmac_f32_e32 v186, v142, v142
	v_fmac_f32_e32 v186, v143, v143
	ds_bpermute_b32 v128, v237, v186
	v_lshl_add_u64 v[130:131], s[36:37], 0, v[176:177]
	v_lshl_add_u64 v[130:131], v[168:169], 1, v[130:131]
	global_store_dwordx4 v[130:131], v[132:135], off
	global_store_dwordx4 v[130:131], v[136:139], off offset:256
	s_waitcnt lgkmcnt(0)
	v_add_f32_e32 v128, v186, v128
	ds_bpermute_b32 v129, v238, v128
	s_and_saveexec_b64 s[16:17], s[12:13]
	s_cbranch_execz .LBB0_1177
	s_waitcnt lgkmcnt(0)
	v_add_f32_e32 v130, v128, v129
	v_lshl_add_u64 v[128:129], v[166:167], 2, s[4:5]
	global_atomic_add_f32 v[128:129], v130, off offset:576
.LBB0_1177:
	s_or_b64 exec, exec, s[16:17]
	s_waitcnt vmcnt(4)
	s_mov_b64 s[16:17], 0x50000
	v_lshl_add_u64 v[182:183], v[174:175], 0, s[16:17]
	s_mov_b64 s[16:17], 0x58000
	s_waitcnt lgkmcnt(0)
	v_lshl_add_u64 v[128:129], v[172:173], 0, v[182:183]
	v_lshl_add_u64 v[174:175], v[174:175], 0, s[16:17]
	v_lshl_add_u64 v[128:129], v[172:173], 0, v[174:175]
	s_nop 0
	v_mov_b32_e32 v140, v64
	v_mov_b32_e32 v141, v65
	v_mov_b32_e32 v142, v66
	v_mov_b32_e32 v143, v67
	v_mov_b32_e32 v136, v68
	v_mov_b32_e32 v137, v69
	v_mov_b32_e32 v138, v70
	v_mov_b32_e32 v139, v71
	v_mov_b32_e32 v132, v72
	v_mov_b32_e32 v133, v73
	v_mov_b32_e32 v134, v74
	v_mov_b32_e32 v135, v75
	v_mov_b32_e32 v128, v76
	v_mov_b32_e32 v129, v77
	v_mov_b32_e32 v130, v78
	v_mov_b32_e32 v131, v79
	v_mov_b32_e32 v172, 0
	v_mov_b32_e32 v173, 0
	v_mov_b32_e32 v176, 0
	v_mov_b32_e32 v177, 0
	v_mov_b32_e32 v178, 0
	v_mov_b32_e32 v179, 0
	v_mov_b32_e32 v180, 0
	v_mov_b32_e32 v181, 0
	v_mov_b32_e32 v184, 0
	v_mov_b32_e32 v185, 0
	v_mov_b32_e32 v186, 0
	v_mov_b32_e32 v187, 0
	v_mov_b32_e32 v188, 0
	v_mov_b32_e32 v189, 0
	v_mov_b32_e32 v190, 0
	v_mov_b32_e32 v191, 0
	v_mov_b32_e32 v192, 0
	v_mov_b32_e32 v193, 0
	v_mov_b32_e32 v194, 0
	v_mov_b32_e32 v195, 0
	v_mov_b32_e32 v196, 0
	v_mov_b32_e32 v197, 0
	v_mov_b32_e32 v198, 0
	v_mov_b32_e32 v199, 0
	v_mov_b32_e32 v200, 0
	v_mov_b32_e32 v201, 0
	v_mov_b32_e32 v202, 0
	v_mov_b32_e32 v203, 0
	v_mov_b32_e32 v204, 0
	v_mov_b32_e32 v205, 0
	v_mov_b32_e32 v206, 0
	v_mov_b32_e32 v207, 0
	s_and_saveexec_b64 s[16:17], vcc
	s_cbranch_execz .LBB0_1179
	s_mov_b64 s[38:39], 0x2800
	v_lshl_add_u64 v[180:181], v[170:171], 0, s[38:39]
	s_mov_b64 s[38:39], 0x3800
	v_lshl_add_u64 v[188:189], v[170:171], 0, s[38:39]
	s_mov_b64 s[38:39], 0x2c00
	v_lshl_add_u64 v[190:191], v[170:171], 0, s[38:39]
	s_mov_b64 s[38:39], 0x3c00
	v_lshl_add_u64 v[192:193], v[170:171], 0, s[38:39]
	v_mov_b32_e32 v170, v96
	v_mov_b32_e32 v171, v97
	v_mov_b32_e32 v172, v98
	v_mov_b32_e32 v173, v99
	v_mov_b32_e32 v176, v100
	v_mov_b32_e32 v177, v101
	v_mov_b32_e32 v178, v102
	v_mov_b32_e32 v179, v103
	v_mov_b32_e32 v184, v104
	v_mov_b32_e32 v185, v105
	v_mov_b32_e32 v186, v106
	v_mov_b32_e32 v187, v107
	v_mov_b32_e32 v208, v108
	v_mov_b32_e32 v209, v109
	v_mov_b32_e32 v210, v110
	v_mov_b32_e32 v211, v111
	s_nop 0
	v_lshlrev_b32_e32 v204, 16, v170
	v_and_b32_e32 v205, 0xffff0000, v170
	v_lshlrev_b32_e32 v206, 16, v171
	v_and_b32_e32 v207, 0xffff0000, v171
	v_lshlrev_b32_e32 v200, 16, v172
	v_and_b32_e32 v201, 0xffff0000, v172
	v_lshlrev_b32_e32 v202, 16, v173
	v_and_b32_e32 v203, 0xffff0000, v173
	v_lshlrev_b32_e32 v196, 16, v176
	v_and_b32_e32 v197, 0xffff0000, v176
	v_lshlrev_b32_e32 v198, 16, v177
	v_and_b32_e32 v199, 0xffff0000, v177
	v_lshlrev_b32_e32 v192, 16, v178
	v_and_b32_e32 v193, 0xffff0000, v178
	v_lshlrev_b32_e32 v194, 16, v179
	v_and_b32_e32 v195, 0xffff0000, v179
	v_lshlrev_b32_e32 v188, 16, v184
	v_and_b32_e32 v189, 0xffff0000, v184
	v_lshlrev_b32_e32 v190, 16, v185
	v_and_b32_e32 v191, 0xffff0000, v185
	v_lshlrev_b32_e32 v184, 16, v186
	v_and_b32_e32 v185, 0xffff0000, v186
	v_lshlrev_b32_e32 v186, 16, v187
	v_and_b32_e32 v187, 0xffff0000, v187
	v_lshlrev_b32_e32 v178, 16, v208
	v_and_b32_e32 v179, 0xffff0000, v208
	v_lshlrev_b32_e32 v180, 16, v209
	v_and_b32_e32 v181, 0xffff0000, v209
	v_lshlrev_b32_e32 v172, 16, v210
	v_and_b32_e32 v173, 0xffff0000, v210
	v_lshlrev_b32_e32 v176, 16, v211
	v_and_b32_e32 v177, 0xffff0000, v211
; DI unsigned cvt_pk(float lo, float hi) { unsigned r; asm("v_cvt_pk_bf16_f32 %0, %1, %2" : "=v"(r) : "v"(lo), "v"(hi)); return r; }
;     __device__ __forceinline__ void operator()(const f32x4 (&acc)[2][2][4][2], const Unit& u, int wr, int wc, int fr, int fq) const {
;     ...
; #pragma unroll
;                 for (int mm = 0; mm < 2; ++mm) {
;                     const int m = mp * 2 + mm;
;                     const int row = row0 + ai * HALF + m * 16;
;                     float s = 0.f;
; #pragma unroll
;                     for (int bj = 0; bj < 2; ++bj) {
;                         u32x4* px = (u32x4*)(X + (size_t)row * DM + col0 + bj * HALF);
;                         float xo[8]; unpack8(xin[mm][bj], xo);
;                         const f32x4 a0 = acc[ai][bj][m][0] + pv[mm][bj][0], a1 = acc[ai][bj][m][1] + pv[mm][bj][1];
;                         u32x4 w;
;                         w.x = cvt_pk(xo[0] + scale * a0[0], xo[1] + scale * a0[1]); w.y = cvt_pk(xo[2] + scale * a0[2], xo[3] + scale * a0[3]);
;                         w.z = cvt_pk(xo[4] + scale * a1[0], xo[5] + scale * a1[1]); w.w = cvt_pk(xo[6] + scale * a1[2], xo[7] + scale * a1[3]);
;                         *px = w;
;                         float xn[8]; unpack8(w, xn);
; #pragma unroll
;                         for (int j = 0; j < 8; ++j) s += xn[j] * xn[j];
;                     }
;                     s += __shfl_xor(s, 16); s += __shfl_xor(s, 32);
;                     if (fq == 0) unsafeAtomicAdd(ssn + row, s);
;                 }
.LBB0_1179:
	s_or_b64 exec, exec, s[16:17]
	v_lshlrev_b32_e32 v208, 16, v140
	v_and_b32_e32 v209, 0xffff0000, v140
	v_lshlrev_b32_e32 v210, 16, v141
	v_and_b32_e32 v211, 0xffff0000, v141
	v_pk_add_f32 v[140:141], v[44:45], v[204:205]
	v_lshlrev_b32_e32 v214, 16, v142
	v_and_b32_e32 v215, 0xffff0000, v142
	v_lshlrev_b32_e32 v244, 16, v143
	v_and_b32_e32 v245, 0xffff0000, v143
	v_pk_add_f32 v[142:143], v[46:47], v[206:207]
	v_add_f32_e32 v140, v140, v208
	v_add_f32_e32 v141, v141, v209
	v_pk_add_f32 v[200:201], v[40:41], v[200:201]
	v_cvt_pk_bf16_f32 v140, v140, v141
	v_add_f32_e32 v141, v142, v210
	v_add_f32_e32 v142, v143, v211
	v_pk_add_f32 v[170:171], v[42:43], v[202:203]
	v_cvt_pk_bf16_f32 v141, v141, v142
	v_add_f32_e32 v142, v200, v214
	v_add_f32_e32 v143, v201, v215
	v_cvt_pk_bf16_f32 v142, v142, v143
	v_add_f32_e32 v143, v170, v244
	v_add_f32_e32 v170, v171, v245
	v_and_b32_e32 v171, 0xffff0000, v140
	v_cvt_pk_bf16_f32 v143, v143, v170
	v_lshlrev_b32_e32 v170, 16, v140
	v_mul_f32_e32 v206, v171, v171
	v_lshlrev_b32_e32 v200, 16, v141
	v_fmac_f32_e32 v206, v170, v170
	v_and_b32_e32 v201, 0xffff0000, v141
	v_fmac_f32_e32 v206, v200, v200
	v_lshlrev_b32_e32 v202, 16, v142
	v_fmac_f32_e32 v206, v201, v201
	v_and_b32_e32 v203, 0xffff0000, v142
	v_fmac_f32_e32 v206, v202, v202
	v_lshlrev_b32_e32 v204, 16, v143
	v_fmac_f32_e32 v206, v203, v203
	v_lshlrev_b32_e32 v200, 16, v136
	v_and_b32_e32 v201, 0xffff0000, v136
	v_lshlrev_b32_e32 v202, 16, v137
	v_and_b32_e32 v203, 0xffff0000, v137
	v_pk_add_f32 v[136:137], v[14:15], v[198:199]
	v_and_b32_e32 v205, 0xffff0000, v143
	v_fmac_f32_e32 v206, v204, v204
	v_lshlrev_b32_e32 v204, 16, v138
	v_pk_add_f32 v[170:171], v[10:11], v[194:195]
	v_pk_add_f32 v[194:195], v[8:9], v[192:193]
	v_add_f32_e32 v136, v136, v202
	v_fmac_f32_e32 v206, v205, v205
	v_and_b32_e32 v205, 0xffff0000, v138
	v_lshlrev_b32_e32 v207, 16, v139
	v_add_f32_e32 v137, v137, v203
	v_cvt_pk_bf16_f32 v193, v136, v137
	v_add_f32_e32 v136, v194, v204
	v_and_b32_e32 v208, 0xffff0000, v139
	v_pk_add_f32 v[138:139], v[12:13], v[196:197]
	v_add_f32_e32 v137, v195, v205
	v_cvt_pk_bf16_f32 v194, v136, v137
	v_add_f32_e32 v136, v170, v207
	v_add_f32_e32 v138, v138, v200
	v_add_f32_e32 v139, v139, v201
	v_cvt_pk_bf16_f32 v192, v138, v139
	v_add_f32_e32 v137, v171, v208
	v_cvt_pk_bf16_f32 v195, v136, v137
	v_lshlrev_b32_e32 v136, 16, v192
	v_and_b32_e32 v137, 0xffff0000, v192
	v_fmac_f32_e32 v206, v136, v136
	v_lshlrev_b32_e32 v138, 16, v193
	v_fmac_f32_e32 v206, v137, v137
	v_and_b32_e32 v139, 0xffff0000, v193
	v_fmac_f32_e32 v206, v138, v138
	v_lshlrev_b32_e32 v170, 16, v194
	v_fmac_f32_e32 v206, v139, v139
	v_and_b32_e32 v171, 0xffff0000, v194
	v_fmac_f32_e32 v206, v170, v170
	v_lshlrev_b32_e32 v196, 16, v195
	v_fmac_f32_e32 v206, v171, v171
	v_and_b32_e32 v197, 0xffff0000, v195
	v_fmac_f32_e32 v206, v196, v196
	v_fmac_f32_e32 v206, v197, v197
	ds_bpermute_b32 v136, v237, v206
	v_lshl_add_u64 v[138:139], s[36:37], 0, v[182:183]
	v_lshl_add_u64 v[138:139], v[168:169], 1, v[138:139]
	global_store_dwordx4 v[138:139], v[140:143], off
	global_store_dwordx4 v[138:139], v[192:195], off offset:256
	s_waitcnt lgkmcnt(0)
	v_add_f32_e32 v136, v206, v136
	ds_bpermute_b32 v137, v238, v136
	s_and_saveexec_b64 s[16:17], s[12:13]
	s_cbranch_execz .LBB0_1181
	s_waitcnt lgkmcnt(0)
	v_add_f32_e32 v138, v136, v137
	v_lshl_add_u64 v[136:137], v[166:167], 2, s[4:5]
	global_atomic_add_f32 v[136:137], v138, off offset:640
.LBB0_1181:
	s_or_b64 exec, exec, s[16:17]
	v_lshlrev_b32_e32 v140, 16, v132
	v_and_b32_e32 v141, 0xffff0000, v132
	v_lshlrev_b32_e32 v142, 16, v133
	v_and_b32_e32 v143, 0xffff0000, v133
	v_pk_add_f32 v[132:133], v[36:37], v[188:189]
	v_lshlrev_b32_e32 v170, 16, v134
	v_and_b32_e32 v171, 0xffff0000, v134
	v_lshlrev_b32_e32 v182, 16, v135
	v_and_b32_e32 v183, 0xffff0000, v135
	v_pk_add_f32 v[134:135], v[38:39], v[190:191]
	v_add_f32_e32 v132, v132, v140
	v_add_f32_e32 v133, v133, v141
	v_pk_add_f32 v[138:139], v[32:33], v[184:185]
	v_cvt_pk_bf16_f32 v132, v132, v133
	v_add_f32_e32 v133, v134, v142
	v_add_f32_e32 v134, v135, v143
	s_waitcnt lgkmcnt(0)
	v_pk_add_f32 v[136:137], v[34:35], v[186:187]
	v_cvt_pk_bf16_f32 v133, v133, v134
	v_add_f32_e32 v134, v138, v170
	v_add_f32_e32 v135, v139, v171
	v_cvt_pk_bf16_f32 v134, v134, v135
	v_add_f32_e32 v135, v136, v182
	v_add_f32_e32 v136, v137, v183
	v_and_b32_e32 v137, 0xffff0000, v132
	v_cvt_pk_bf16_f32 v135, v135, v136
	v_lshlrev_b32_e32 v136, 16, v132
	v_mul_f32_e32 v170, v137, v137
	v_lshlrev_b32_e32 v138, 16, v133
	v_fmac_f32_e32 v170, v136, v136
	v_and_b32_e32 v139, 0xffff0000, v133
	v_fmac_f32_e32 v170, v138, v138
	v_lshlrev_b32_e32 v140, 16, v134
	v_fmac_f32_e32 v170, v139, v139
	v_and_b32_e32 v141, 0xffff0000, v134
	v_fmac_f32_e32 v170, v140, v140
	v_lshlrev_b32_e32 v142, 16, v135
	v_fmac_f32_e32 v170, v141, v141
	v_and_b32_e32 v143, 0xffff0000, v135
	v_fmac_f32_e32 v170, v142, v142
	v_fmac_f32_e32 v170, v143, v143
	v_lshlrev_b32_e32 v136, 16, v128
	v_and_b32_e32 v137, 0xffff0000, v128
	v_lshlrev_b32_e32 v142, 16, v129
	v_and_b32_e32 v143, 0xffff0000, v129
	v_pk_add_f32 v[128:129], v[6:7], v[180:181]
	v_lshlrev_b32_e32 v171, 16, v130
	v_and_b32_e32 v182, 0xffff0000, v130
	v_lshlrev_b32_e32 v183, 16, v131
	v_and_b32_e32 v184, 0xffff0000, v131
	v_pk_add_f32 v[130:131], v[4:5], v[178:179]
	v_pk_add_f32 v[138:139], v[0:1], v[172:173]
	v_add_f32_e32 v128, v128, v142
	v_pk_add_f32 v[140:141], v[2:3], v[176:177]
	v_add_f32_e32 v131, v131, v137
	v_add_f32_e32 v129, v129, v143
	v_cvt_pk_bf16_f32 v137, v128, v129
	v_add_f32_e32 v128, v138, v171
	v_add_f32_e32 v129, v139, v182
	v_cvt_pk_bf16_f32 v138, v128, v129
	v_add_f32_e32 v128, v140, v183
	v_add_f32_e32 v130, v130, v136
	v_cvt_pk_bf16_f32 v136, v130, v131
	v_add_f32_e32 v129, v141, v184
	v_cvt_pk_bf16_f32 v139, v128, v129
	v_lshlrev_b32_e32 v128, 16, v136
	v_and_b32_e32 v129, 0xffff0000, v136
	v_fmac_f32_e32 v170, v128, v128
	v_lshlrev_b32_e32 v130, 16, v137
	v_fmac_f32_e32 v170, v129, v129
	v_and_b32_e32 v131, 0xffff0000, v137
	v_fmac_f32_e32 v170, v130, v130
	v_lshlrev_b32_e32 v140, 16, v138
	v_fmac_f32_e32 v170, v131, v131
	v_and_b32_e32 v141, 0xffff0000, v138
	v_fmac_f32_e32 v170, v140, v140
	v_lshlrev_b32_e32 v142, 16, v139
	v_fmac_f32_e32 v170, v141, v141
	v_and_b32_e32 v143, 0xffff0000, v139
	v_fmac_f32_e32 v170, v142, v142
	v_fmac_f32_e32 v170, v143, v143
	ds_bpermute_b32 v128, v237, v170
	v_lshl_add_u64 v[130:131], s[36:37], 0, v[174:175]
	v_lshl_add_u64 v[130:131], v[168:169], 1, v[130:131]
	global_store_dwordx4 v[130:131], v[132:135], off
	global_store_dwordx4 v[130:131], v[136:139], off offset:256
	s_waitcnt lgkmcnt(0)
	v_add_f32_e32 v128, v170, v128
	ds_bpermute_b32 v129, v238, v128
	s_and_saveexec_b64 s[16:17], s[12:13]
	s_cbranch_execz .LBB0_1183
	s_waitcnt lgkmcnt(0)
	v_add_f32_e32 v130, v128, v129
	v_lshl_add_u64 v[128:129], v[166:167], 2, s[4:5]
	global_atomic_add_f32 v[128:129], v130, off offset:704

;     __device__ __forceinline__ void operator()(const f32x4 (&acc)[2][2][4][2], const Unit& u, int wr, int wc, int fr, int fq) const {
;     ...
;                 u32x4 xin[2][2];
; #pragma unroll
;                 for (int mm = 0; mm < 2; ++mm)
; #pragma unroll
;                     for (int bj = 0; bj < 2; ++bj) xin[mm][bj] = *(const u32x4*)(X + (size_t)(row0 + ai * HALF + (mp * 2 + mm) * 16) * DM + col0 + bj * HALF);
;                 f32x4 pv[2][2][2];
; #pragma unroll
;                 for (int mm = 0; mm < 2; ++mm)
; #pragma unroll
;                     for (int bj = 0; bj < 2; ++bj)
; #pragma unroll
;                         for (int n = 0; n < 2; ++n) pv[mm][bj][n] = (f32x4){0.f, 0.f, 0.f, 0.f};
;                 if (src) {
;                     u32x4 pc[2][2];
;     ...
;                     asm volatile("global_load_dwordx4 %0, %4, off sc1\n\tglobal_load_dwordx4 %1, %5, off sc1\n\tglobal_load_dwordx4 %2, %6, off sc1\n\tglobal_load_dwordx4 %3, %7, off sc1\n\ts_waitcnt vmcnt(0)"
;                                  : "=&v"(pc[0][0]), "=&v"(pc[0][1]), "=&v"(pc[1][0]), "=&v"(pc[1][1])
;                                  : "v"(src + CI(0, 0)), "v"(src + CI(0, 1)), "v"(src + CI(1, 0)), "v"(src + CI(1, 1))
;                                  : "memory");
;     ...
; #pragma unroll
;                     for (int mm = 0; mm < 2; ++mm)
; #pragma unroll
;                         for (int bj = 0; bj < 2; ++bj) { float f[8]; unpack8(pc[mm][bj], f); pv[mm][bj][0] = (f32x4){f[0], f[1], f[2], f[3]}; pv[mm][bj][1] = (f32x4){f[4], f[5], f[6], f[7]}; }
;                 }
; #pragma unroll
;                 for (int mm = 0; mm < 2; ++mm) {
;                     const int m = mp * 2 + mm;
;                     const int row = row0 + ai * HALF + m * 16;
;                     float s = 0.f;
; #pragma unroll
;                     for (int bj = 0; bj < 2; ++bj) {
;                         u32x4* px = (u32x4*)(X + (size_t)row * DM + col0 + bj * HALF);
;                         float xo[8]; unpack8(xin[mm][bj], xo);
;                         const f32x4 a0 = acc[ai][bj][m][0] + pv[mm][bj][0], a1 = acc[ai][bj][m][1] + pv[mm][bj][1];
;                         u32x4 w;
;                         w.x = cvt_pk(xo[0] + scale * a0[0], xo[1] + scale * a0[1]); w.y = cvt_pk(xo[2] + scale * a0[2], xo[3] + scale * a0[3]);
.LBB0_1412:
	s_or_b64 exec, exec, s[12:13]
	s_waitcnt vmcnt(0)
	s_mov_b64 s[30:31], 0x40000
	v_lshl_add_u64 v[250:251], v[174:175], 0, s[30:31]
	v_lshl_add_u64 v[250:251], v[172:173], 0, v[250:251]
	global_load_dwordx4 v[80:83], v[250:251], off
	global_load_dwordx4 v[84:87], v[250:251], off offset:256
	s_mov_b64 s[30:31], 0x48000
	v_lshl_add_u64 v[252:253], v[174:175], 0, s[30:31]
	v_lshl_add_u64 v[252:253], v[172:173], 0, v[252:253]
	global_load_dwordx4 v[88:91], v[252:253], off
	global_load_dwordx4 v[92:95], v[252:253], off offset:256
	s_and_saveexec_b64 s[12:13], vcc
	s_mov_b64 s[30:31], 0x2000
	v_lshl_add_u64 v[250:251], v[170:171], 0, s[30:31]
	global_load_dwordx4 v[112:115], v[250:251], off sc1
	s_mov_b64 s[30:31], 0x3000
	v_lshl_add_u64 v[252:253], v[170:171], 0, s[30:31]
	global_load_dwordx4 v[116:119], v[252:253], off sc1
	s_mov_b64 s[30:31], 0x2400
	v_lshl_add_u64 v[250:251], v[170:171], 0, s[30:31]
	global_load_dwordx4 v[120:123], v[250:251], off sc1
	s_mov_b64 s[30:31], 0x3400
	v_lshl_add_u64 v[252:253], v[170:171], 0, s[30:31]
	global_load_dwordx4 v[124:127], v[252:253], off sc1
	s_or_b64 exec, exec, s[12:13]
	v_lshlrev_b32_e32 v214, 16, v140
	v_and_b32_e32 v215, 0xffff0000, v140
	v_lshlrev_b32_e32 v244, 16, v141
	v_and_b32_e32 v245, 0xffff0000, v141
	v_and_b32_e32 v247, 0xffff0000, v142
	v_pk_add_f32 v[140:141], v[108:109], v[208:209]
	v_pk_add_f32 v[204:205], v[104:105], v[204:205]
	v_lshlrev_b32_e32 v246, 16, v142
	v_fmac_f32_e32 v214, 0.5, v140
	v_fmac_f32_e32 v215, 0.5, v141
	v_cvt_pk_bf16_f32 v140, v214, v215
	v_fmac_f32_e32 v247, 0.5, v205
	v_and_b32_e32 v205, 0xffff0000, v140
	v_lshlrev_b32_e32 v248, 16, v143
	v_and_b32_e32 v249, 0xffff0000, v143
	v_pk_add_f32 v[142:143], v[110:111], v[210:211]
	v_pk_add_f32 v[206:207], v[106:107], v[206:207]
	v_fmac_f32_e32 v246, 0.5, v204
	v_lshlrev_b32_e32 v204, 16, v140
	v_mul_f32_e32 v205, v205, v205
	v_fmac_f32_e32 v244, 0.5, v142
	v_fmac_f32_e32 v245, 0.5, v143
	v_cvt_pk_bf16_f32 v141, v244, v245
	v_fmac_f32_e32 v248, 0.5, v206
	v_lshlrev_b32_e32 v206, 16, v141
	v_fmac_f32_e32 v205, v204, v204
	v_fmac_f32_e32 v249, 0.5, v207
	v_and_b32_e32 v207, 0xffff0000, v141
	v_fmac_f32_e32 v205, v206, v206
	v_cvt_pk_bf16_f32 v142, v246, v247
	v_fmac_f32_e32 v205, v207, v207
	v_lshlrev_b32_e32 v208, 16, v142
	v_and_b32_e32 v209, 0xffff0000, v142
	v_fmac_f32_e32 v205, v208, v208
	v_cvt_pk_bf16_f32 v143, v248, v249
	v_fmac_f32_e32 v205, v209, v209
	v_lshlrev_b32_e32 v210, 16, v143
	v_and_b32_e32 v211, 0xffff0000, v143
	v_fmac_f32_e32 v205, v210, v210
	v_fmac_f32_e32 v205, v211, v211
	v_lshlrev_b32_e32 v204, 16, v136
	v_and_b32_e32 v206, 0xffff0000, v136
	v_lshlrev_b32_e32 v207, 16, v137
	v_and_b32_e32 v208, 0xffff0000, v137
	v_lshlrev_b32_e32 v209, 16, v138
	v_and_b32_e32 v210, 0xffff0000, v138
	v_lshlrev_b32_e32 v211, 16, v139
	v_and_b32_e32 v214, 0xffff0000, v139
	v_pk_add_f32 v[136:137], v[78:79], v[202:203]
	v_pk_add_f32 v[138:139], v[76:77], v[200:201]
	v_pk_add_f32 v[200:201], v[74:75], v[198:199]
	v_pk_add_f32 v[198:199], v[72:73], v[196:197]
	v_fmac_f32_e32 v204, 0.5, v138
	v_fmac_f32_e32 v206, 0.5, v139
	v_cvt_pk_bf16_f32 v196, v204, v206
	v_fmac_f32_e32 v207, 0.5, v136
	v_lshlrev_b32_e32 v136, 16, v196
	v_fmac_f32_e32 v208, 0.5, v137
	v_and_b32_e32 v137, 0xffff0000, v196
	v_fmac_f32_e32 v205, v136, v136
	v_cvt_pk_bf16_f32 v197, v207, v208
	v_fmac_f32_e32 v205, v137, v137
	v_lshlrev_b32_e32 v138, 16, v197
	v_and_b32_e32 v139, 0xffff0000, v197
	v_fmac_f32_e32 v205, v138, v138
	v_fmac_f32_e32 v209, 0.5, v198
	v_fmac_f32_e32 v210, 0.5, v199
	v_cvt_pk_bf16_f32 v198, v209, v210
	v_fmac_f32_e32 v211, 0.5, v200
	v_lshlrev_b32_e32 v200, 16, v198
	v_fmac_f32_e32 v205, v139, v139
	v_fmac_f32_e32 v214, 0.5, v201
	v_and_b32_e32 v201, 0xffff0000, v198
	v_fmac_f32_e32 v205, v200, v200
	v_cvt_pk_bf16_f32 v199, v211, v214
	v_fmac_f32_e32 v205, v201, v201
	v_lshlrev_b32_e32 v202, 16, v199
	v_and_b32_e32 v203, 0xffff0000, v199
	v_fmac_f32_e32 v205, v202, v202
	v_fmac_f32_e32 v205, v203, v203
	ds_bpermute_b32 v136, v237, v205
	v_lshl_add_u64 v[138:139], s[28:29], 0, v[186:187]
	v_lshl_add_u64 v[138:139], v[168:169], 1, v[138:139]
	global_store_dwordx4 v[138:139], v[140:143], off
	global_store_dwordx4 v[138:139], v[196:199], off offset:256
	s_waitcnt lgkmcnt(0)
	v_add_f32_e32 v136, v205, v136
	ds_bpermute_b32 v137, v238, v136
	s_and_saveexec_b64 s[12:13], s[8:9]
	s_cbranch_execz .LBB0_1414
	s_waitcnt lgkmcnt(0)
	v_add_f32_e32 v138, v136, v137
	v_lshl_add_u64 v[136:137], v[166:167], 2, s[14:15]
	global_atomic_add_f32 v[136:137], v138, off offset:128
; DI unsigned cvt_pk(float lo, float hi) { unsigned r; asm("v_cvt_pk_bf16_f32 %0, %1, %2" : "=v"(r) : "v"(lo), "v"(hi)); return r; }
;     __device__ __forceinline__ void operator()(const f32x4 (&acc)[2][2][4][2], const Unit& u, int wr, int wc, int fr, int fq) const {
;     ...
; #pragma unroll
;                 for (int mm = 0; mm < 2; ++mm) {
;                     const int m = mp * 2 + mm;
;                     const int row = row0 + ai * HALF + m * 16;
;                     float s = 0.f;
; #pragma unroll
;                     for (int bj = 0; bj < 2; ++bj) {
;                         u32x4* px = (u32x4*)(X + (size_t)row * DM + col0 + bj * HALF);
;                         float xo[8]; unpack8(xin[mm][bj], xo);
;                         const f32x4 a0 = acc[ai][bj][m][0] + pv[mm][bj][0], a1 = acc[ai][bj][m][1] + pv[mm][bj][1];
;                         u32x4 w;
;                         w.x = cvt_pk(xo[0] + scale * a0[0], xo[1] + scale * a0[1]); w.y = cvt_pk(xo[2] + scale * a0[2], xo[3] + scale * a0[3]);
;                         w.z = cvt_pk(xo[4] + scale * a1[0], xo[5] + scale * a1[1]); w.w = cvt_pk(xo[6] + scale * a1[2], xo[7] + scale * a1[3]);
;                         *px = w;
;                         float xn[8]; unpack8(w, xn);
; #pragma unroll
;                         for (int j = 0; j < 8; ++j) s += xn[j] * xn[j];
;                     }
;                     s += __shfl_xor(s, 16); s += __shfl_xor(s, 32);
;                     if (fq == 0) unsafeAtomicAdd(ssn + row, s);
;                 }
.LBB0_1414:
	s_or_b64 exec, exec, s[12:13]
	v_lshlrev_b32_e32 v140, 16, v132
	v_and_b32_e32 v141, 0xffff0000, v132
	v_lshlrev_b32_e32 v142, 16, v133
	v_and_b32_e32 v143, 0xffff0000, v133
	v_lshlrev_b32_e32 v186, 16, v134
	v_and_b32_e32 v197, 0xffff0000, v135
	v_pk_add_f32 v[132:133], v[100:101], v[192:193]
	s_waitcnt lgkmcnt(0)
	v_pk_add_f32 v[136:137], v[98:99], v[190:191]
	v_pk_add_f32 v[138:139], v[96:97], v[188:189]
	v_and_b32_e32 v187, 0xffff0000, v134
	v_lshlrev_b32_e32 v196, 16, v135
	v_pk_add_f32 v[134:135], v[102:103], v[194:195]
	v_fmac_f32_e32 v140, 0.5, v132
	v_fmac_f32_e32 v141, 0.5, v133
	v_cvt_pk_bf16_f32 v132, v140, v141
	v_fmac_f32_e32 v186, 0.5, v138
	v_fmac_f32_e32 v197, 0.5, v137
	v_and_b32_e32 v137, 0xffff0000, v132
	v_fmac_f32_e32 v142, 0.5, v134
	v_fmac_f32_e32 v187, 0.5, v139
	v_cvt_pk_bf16_f32 v134, v186, v187
	v_fmac_f32_e32 v196, 0.5, v136
	v_lshlrev_b32_e32 v136, 16, v132
	v_mul_f32_e32 v186, v137, v137
	v_fmac_f32_e32 v143, 0.5, v135
	v_cvt_pk_bf16_f32 v133, v142, v143
	v_fmac_f32_e32 v186, v136, v136
	v_lshlrev_b32_e32 v138, 16, v133
	v_and_b32_e32 v139, 0xffff0000, v133
	v_fmac_f32_e32 v186, v138, v138
	v_lshlrev_b32_e32 v140, 16, v134
	v_fmac_f32_e32 v186, v139, v139
	v_and_b32_e32 v141, 0xffff0000, v134
	v_fmac_f32_e32 v186, v140, v140
	v_cvt_pk_bf16_f32 v135, v196, v197
	v_fmac_f32_e32 v186, v141, v141
	v_lshlrev_b32_e32 v142, 16, v135
	v_and_b32_e32 v143, 0xffff0000, v135
	v_fmac_f32_e32 v186, v142, v142
	v_lshlrev_b32_e32 v136, 16, v128
	v_lshlrev_b32_e32 v187, 16, v130
	v_and_b32_e32 v188, 0xffff0000, v130
	v_lshlrev_b32_e32 v189, 16, v131
	v_and_b32_e32 v190, 0xffff0000, v131
	v_pk_add_f32 v[130:131], v[68:69], v[182:183]
	v_fmac_f32_e32 v186, v143, v143
	v_and_b32_e32 v137, 0xffff0000, v128
	v_lshlrev_b32_e32 v142, 16, v129
	v_and_b32_e32 v143, 0xffff0000, v129
	v_pk_add_f32 v[128:129], v[70:71], v[184:185]
	v_fmac_f32_e32 v136, 0.5, v130
	v_fmac_f32_e32 v137, 0.5, v131
	v_cvt_pk_bf16_f32 v136, v136, v137
	v_fmac_f32_e32 v142, 0.5, v128
	v_lshlrev_b32_e32 v128, 16, v136
	v_fmac_f32_e32 v143, 0.5, v129
	v_and_b32_e32 v129, 0xffff0000, v136
	v_fmac_f32_e32 v186, v128, v128
	v_cvt_pk_bf16_f32 v137, v142, v143
	v_fmac_f32_e32 v186, v129, v129
	v_lshlrev_b32_e32 v130, 16, v137
	v_pk_add_f32 v[140:141], v[66:67], v[180:181]
	v_pk_add_f32 v[138:139], v[64:65], v[178:179]
	v_and_b32_e32 v131, 0xffff0000, v137
	v_fmac_f32_e32 v186, v130, v130
	v_fmac_f32_e32 v187, 0.5, v138
	v_fmac_f32_e32 v188, 0.5, v139
	v_cvt_pk_bf16_f32 v138, v187, v188
	v_fmac_f32_e32 v189, 0.5, v140
	v_lshlrev_b32_e32 v140, 16, v138
	v_fmac_f32_e32 v186, v131, v131
	v_fmac_f32_e32 v190, 0.5, v141
	v_and_b32_e32 v141, 0xffff0000, v138
	v_fmac_f32_e32 v186, v140, v140
	v_cvt_pk_bf16_f32 v139, v189, v190
	v_fmac_f32_e32 v186, v141, v141
	v_lshlrev_b32_e32 v142, 16, v139
	v_and_b32_e32 v143, 0xffff0000, v139
	v_fmac_f32_e32 v186, v142, v142
	v_fmac_f32_e32 v186, v143, v143
	ds_bpermute_b32 v128, v237, v186
	v_lshl_add_u64 v[130:131], s[28:29], 0, v[176:177]
	v_lshl_add_u64 v[130:131], v[168:169], 1, v[130:131]
	global_store_dwordx4 v[130:131], v[132:135], off
	global_store_dwordx4 v[130:131], v[136:139], off offset:256
	s_waitcnt lgkmcnt(0)
	v_add_f32_e32 v128, v186, v128
	ds_bpermute_b32 v129, v238, v128
	s_and_saveexec_b64 s[12:13], s[8:9]
	s_cbranch_execz .LBB0_1416
	s_waitcnt lgkmcnt(0)
	v_add_f32_e32 v130, v128, v129
	v_lshl_add_u64 v[128:129], v[166:167], 2, s[14:15]
	global_atomic_add_f32 v[128:129], v130, off offset:192

;     __device__ __forceinline__ void operator()(const f32x4 (&acc)[2][2][4][2], const Unit& u, int wr, int wc, int fr, int fq) const {
;     ...
;                 u32x4 xin[2][2];
; #pragma unroll
;                 for (int mm = 0; mm < 2; ++mm)
; #pragma unroll
;                     for (int bj = 0; bj < 2; ++bj) xin[mm][bj] = *(const u32x4*)(X + (size_t)(row0 + ai * HALF + (mp * 2 + mm) * 16) * DM + col0 + bj * HALF);
;                 f32x4 pv[2][2][2];
; #pragma unroll
;                 for (int mm = 0; mm < 2; ++mm)
; #pragma unroll
;                     for (int bj = 0; bj < 2; ++bj)
; #pragma unroll
;                         for (int n = 0; n < 2; ++n) pv[mm][bj][n] = (f32x4){0.f, 0.f, 0.f, 0.f};
;                 if (src) {
;                     u32x4 pc[2][2];
;     ...
;                     asm volatile("global_load_dwordx4 %0, %4, off sc1\n\tglobal_load_dwordx4 %1, %5, off sc1\n\tglobal_load_dwordx4 %2, %6, off sc1\n\tglobal_load_dwordx4 %3, %7, off sc1\n\ts_waitcnt vmcnt(0)"
;                                  : "=&v"(pc[0][0]), "=&v"(pc[0][1]), "=&v"(pc[1][0]), "=&v"(pc[1][1])
;                                  : "v"(src + CI(0, 0)), "v"(src + CI(0, 1)), "v"(src + CI(1, 0)), "v"(src + CI(1, 1))
;                                  : "memory");
;     ...
; #pragma unroll
;                     for (int mm = 0; mm < 2; ++mm)
; #pragma unroll
;                         for (int bj = 0; bj < 2; ++bj) { float f[8]; unpack8(pc[mm][bj], f); pv[mm][bj][0] = (f32x4){f[0], f[1], f[2], f[3]}; pv[mm][bj][1] = (f32x4){f[4], f[5], f[6], f[7]}; }
;                 }
; #pragma unroll
;                 for (int mm = 0; mm < 2; ++mm) {
;                     const int m = mp * 2 + mm;
;                     const int row = row0 + ai * HALF + m * 16;
;                     float s = 0.f;
; #pragma unroll
;                     for (int bj = 0; bj < 2; ++bj) {
;                         u32x4* px = (u32x4*)(X + (size_t)row * DM + col0 + bj * HALF);
;                         float xo[8]; unpack8(xin[mm][bj], xo);
;                         const f32x4 a0 = acc[ai][bj][m][0] + pv[mm][bj][0], a1 = acc[ai][bj][m][1] + pv[mm][bj][1];
;                         u32x4 w;
;                         w.x = cvt_pk(xo[0] + scale * a0[0], xo[1] + scale * a0[1]); w.y = cvt_pk(xo[2] + scale * a0[2], xo[3] + scale * a0[3]);
.LBB0_1418:
	s_or_b64 exec, exec, s[12:13]
	s_mov_b64 s[30:31], 0x50000
	v_lshl_add_u64 v[250:251], v[174:175], 0, s[30:31]
	v_lshl_add_u64 v[250:251], v[172:173], 0, v[250:251]
	global_load_dwordx4 v[64:67], v[250:251], off
	global_load_dwordx4 v[68:71], v[250:251], off offset:256
	s_mov_b64 s[30:31], 0x58000
	v_lshl_add_u64 v[252:253], v[174:175], 0, s[30:31]
	v_lshl_add_u64 v[252:253], v[172:173], 0, v[252:253]
	global_load_dwordx4 v[72:75], v[252:253], off
	global_load_dwordx4 v[76:79], v[252:253], off offset:256
	s_and_saveexec_b64 s[12:13], vcc
	s_mov_b64 s[30:31], 0x2800
	v_lshl_add_u64 v[250:251], v[170:171], 0, s[30:31]
	global_load_dwordx4 v[96:99], v[250:251], off sc1
	s_mov_b64 s[30:31], 0x3800
	v_lshl_add_u64 v[252:253], v[170:171], 0, s[30:31]
	global_load_dwordx4 v[100:103], v[252:253], off sc1
	s_mov_b64 s[30:31], 0x2c00
	v_lshl_add_u64 v[250:251], v[170:171], 0, s[30:31]
	global_load_dwordx4 v[104:107], v[250:251], off sc1
	s_mov_b64 s[30:31], 0x3c00
	v_lshl_add_u64 v[252:253], v[170:171], 0, s[30:31]
	global_load_dwordx4 v[108:111], v[252:253], off sc1
	s_or_b64 exec, exec, s[12:13]
	v_lshlrev_b32_e32 v214, 16, v140
	v_and_b32_e32 v215, 0xffff0000, v140
	v_lshlrev_b32_e32 v244, 16, v141
	v_and_b32_e32 v245, 0xffff0000, v141
	v_and_b32_e32 v247, 0xffff0000, v142
	v_pk_add_f32 v[140:141], v[60:61], v[208:209]
	v_pk_add_f32 v[204:205], v[56:57], v[204:205]
	v_lshlrev_b32_e32 v246, 16, v142
	v_fmac_f32_e32 v214, 0.5, v140
	v_fmac_f32_e32 v215, 0.5, v141
	v_cvt_pk_bf16_f32 v140, v214, v215
	v_fmac_f32_e32 v247, 0.5, v205
	v_and_b32_e32 v205, 0xffff0000, v140
	v_lshlrev_b32_e32 v248, 16, v143
	v_and_b32_e32 v249, 0xffff0000, v143
	v_pk_add_f32 v[142:143], v[62:63], v[210:211]
	v_pk_add_f32 v[206:207], v[58:59], v[206:207]
	v_fmac_f32_e32 v246, 0.5, v204
	v_lshlrev_b32_e32 v204, 16, v140
	v_mul_f32_e32 v205, v205, v205
	v_fmac_f32_e32 v244, 0.5, v142
	v_fmac_f32_e32 v245, 0.5, v143
	v_cvt_pk_bf16_f32 v141, v244, v245
	v_fmac_f32_e32 v248, 0.5, v206
	v_lshlrev_b32_e32 v206, 16, v141
	v_fmac_f32_e32 v205, v204, v204
	v_fmac_f32_e32 v249, 0.5, v207
	v_and_b32_e32 v207, 0xffff0000, v141
	v_fmac_f32_e32 v205, v206, v206
	v_cvt_pk_bf16_f32 v142, v246, v247
	v_fmac_f32_e32 v205, v207, v207
	v_lshlrev_b32_e32 v208, 16, v142
	v_and_b32_e32 v209, 0xffff0000, v142
	v_fmac_f32_e32 v205, v208, v208
	v_cvt_pk_bf16_f32 v143, v248, v249
	v_fmac_f32_e32 v205, v209, v209
	v_lshlrev_b32_e32 v210, 16, v143
	v_and_b32_e32 v211, 0xffff0000, v143
	v_fmac_f32_e32 v205, v210, v210
	v_fmac_f32_e32 v205, v211, v211
	v_lshlrev_b32_e32 v204, 16, v136
	v_and_b32_e32 v206, 0xffff0000, v136
	v_lshlrev_b32_e32 v207, 16, v137
	v_and_b32_e32 v208, 0xffff0000, v137
	v_lshlrev_b32_e32 v209, 16, v138
	v_and_b32_e32 v210, 0xffff0000, v138
	v_lshlrev_b32_e32 v211, 16, v139
	v_and_b32_e32 v214, 0xffff0000, v139
	v_pk_add_f32 v[136:137], v[30:31], v[202:203]
	v_pk_add_f32 v[138:139], v[28:29], v[200:201]
	v_pk_add_f32 v[200:201], v[26:27], v[198:199]
	v_pk_add_f32 v[198:199], v[24:25], v[196:197]
	v_fmac_f32_e32 v204, 0.5, v138
	v_fmac_f32_e32 v206, 0.5, v139
	v_cvt_pk_bf16_f32 v196, v204, v206
	v_fmac_f32_e32 v207, 0.5, v136
	v_lshlrev_b32_e32 v136, 16, v196
	v_fmac_f32_e32 v208, 0.5, v137
	v_and_b32_e32 v137, 0xffff0000, v196
	v_fmac_f32_e32 v205, v136, v136
	v_cvt_pk_bf16_f32 v197, v207, v208
	v_fmac_f32_e32 v205, v137, v137
	v_lshlrev_b32_e32 v138, 16, v197
	v_and_b32_e32 v139, 0xffff0000, v197
	v_fmac_f32_e32 v205, v138, v138
	v_fmac_f32_e32 v209, 0.5, v198
	v_fmac_f32_e32 v210, 0.5, v199
	v_cvt_pk_bf16_f32 v198, v209, v210
	v_fmac_f32_e32 v211, 0.5, v200
	v_lshlrev_b32_e32 v200, 16, v198
	v_fmac_f32_e32 v205, v139, v139
	v_fmac_f32_e32 v214, 0.5, v201
	v_and_b32_e32 v201, 0xffff0000, v198
	v_fmac_f32_e32 v205, v200, v200
	v_cvt_pk_bf16_f32 v199, v211, v214
	v_fmac_f32_e32 v205, v201, v201
	v_lshlrev_b32_e32 v202, 16, v199
	v_and_b32_e32 v203, 0xffff0000, v199
	v_fmac_f32_e32 v205, v202, v202
	v_fmac_f32_e32 v205, v203, v203
	ds_bpermute_b32 v136, v237, v205
	v_lshl_add_u64 v[138:139], s[28:29], 0, v[186:187]
	v_lshl_add_u64 v[138:139], v[168:169], 1, v[138:139]
	global_store_dwordx4 v[138:139], v[140:143], off
	global_store_dwordx4 v[138:139], v[196:199], off offset:256
	s_waitcnt lgkmcnt(0)
	v_add_f32_e32 v136, v205, v136
	ds_bpermute_b32 v137, v238, v136
	s_and_saveexec_b64 s[12:13], s[8:9]
	s_cbranch_execz .LBB0_1420
	s_waitcnt lgkmcnt(0)
	v_add_f32_e32 v138, v136, v137
	v_lshl_add_u64 v[136:137], v[166:167], 2, s[14:15]
	global_atomic_add_f32 v[136:137], v138, off offset:512
; DI unsigned cvt_pk(float lo, float hi) { unsigned r; asm("v_cvt_pk_bf16_f32 %0, %1, %2" : "=v"(r) : "v"(lo), "v"(hi)); return r; }
;     __device__ __forceinline__ void operator()(const f32x4 (&acc)[2][2][4][2], const Unit& u, int wr, int wc, int fr, int fq) const {
;     ...
; #pragma unroll
;                 for (int mm = 0; mm < 2; ++mm) {
;                     const int m = mp * 2 + mm;
;                     const int row = row0 + ai * HALF + m * 16;
;                     float s = 0.f;
; #pragma unroll
;                     for (int bj = 0; bj < 2; ++bj) {
;                         u32x4* px = (u32x4*)(X + (size_t)row * DM + col0 + bj * HALF);
;                         float xo[8]; unpack8(xin[mm][bj], xo);
;                         const f32x4 a0 = acc[ai][bj][m][0] + pv[mm][bj][0], a1 = acc[ai][bj][m][1] + pv[mm][bj][1];
;                         u32x4 w;
;                         w.x = cvt_pk(xo[0] + scale * a0[0], xo[1] + scale * a0[1]); w.y = cvt_pk(xo[2] + scale * a0[2], xo[3] + scale * a0[3]);
;                         w.z = cvt_pk(xo[4] + scale * a1[0], xo[5] + scale * a1[1]); w.w = cvt_pk(xo[6] + scale * a1[2], xo[7] + scale * a1[3]);
;                         *px = w;
;                         float xn[8]; unpack8(w, xn);
; #pragma unroll
;                         for (int j = 0; j < 8; ++j) s += xn[j] * xn[j];
;                     }
;                     s += __shfl_xor(s, 16); s += __shfl_xor(s, 32);
;                     if (fq == 0) unsafeAtomicAdd(ssn + row, s);
;                 }
.LBB0_1420:
	s_or_b64 exec, exec, s[12:13]
	v_lshlrev_b32_e32 v140, 16, v132
	v_and_b32_e32 v141, 0xffff0000, v132
	v_lshlrev_b32_e32 v142, 16, v133
	v_and_b32_e32 v143, 0xffff0000, v133
	v_lshlrev_b32_e32 v186, 16, v134
	v_and_b32_e32 v197, 0xffff0000, v135
	v_pk_add_f32 v[132:133], v[52:53], v[192:193]
	s_waitcnt lgkmcnt(0)
	v_pk_add_f32 v[136:137], v[50:51], v[190:191]
	v_pk_add_f32 v[138:139], v[48:49], v[188:189]
	v_and_b32_e32 v187, 0xffff0000, v134
	v_lshlrev_b32_e32 v196, 16, v135
	v_pk_add_f32 v[134:135], v[54:55], v[194:195]
	v_fmac_f32_e32 v140, 0.5, v132
	v_fmac_f32_e32 v141, 0.5, v133
	v_cvt_pk_bf16_f32 v132, v140, v141
	v_fmac_f32_e32 v186, 0.5, v138
	v_fmac_f32_e32 v197, 0.5, v137
	v_and_b32_e32 v137, 0xffff0000, v132
	v_fmac_f32_e32 v142, 0.5, v134
	v_fmac_f32_e32 v187, 0.5, v139
	v_cvt_pk_bf16_f32 v134, v186, v187
	v_fmac_f32_e32 v196, 0.5, v136
	v_lshlrev_b32_e32 v136, 16, v132
	v_mul_f32_e32 v186, v137, v137
	v_fmac_f32_e32 v143, 0.5, v135
	v_cvt_pk_bf16_f32 v133, v142, v143
	v_fmac_f32_e32 v186, v136, v136
	v_lshlrev_b32_e32 v138, 16, v133
	v_and_b32_e32 v139, 0xffff0000, v133
	v_fmac_f32_e32 v186, v138, v138
	v_lshlrev_b32_e32 v140, 16, v134
	v_fmac_f32_e32 v186, v139, v139
	v_and_b32_e32 v141, 0xffff0000, v134
	v_fmac_f32_e32 v186, v140, v140
	v_cvt_pk_bf16_f32 v135, v196, v197
	v_fmac_f32_e32 v186, v141, v141
	v_lshlrev_b32_e32 v142, 16, v135
	v_and_b32_e32 v143, 0xffff0000, v135
	v_fmac_f32_e32 v186, v142, v142
	v_lshlrev_b32_e32 v136, 16, v128
	v_lshlrev_b32_e32 v187, 16, v130
	v_and_b32_e32 v188, 0xffff0000, v130
	v_lshlrev_b32_e32 v189, 16, v131
	v_and_b32_e32 v190, 0xffff0000, v131
	v_pk_add_f32 v[130:131], v[20:21], v[182:183]
	v_fmac_f32_e32 v186, v143, v143
	v_and_b32_e32 v137, 0xffff0000, v128
	v_lshlrev_b32_e32 v142, 16, v129
	v_and_b32_e32 v143, 0xffff0000, v129
	v_pk_add_f32 v[128:129], v[22:23], v[184:185]
	v_fmac_f32_e32 v136, 0.5, v130
	v_fmac_f32_e32 v137, 0.5, v131
	v_cvt_pk_bf16_f32 v136, v136, v137
	v_fmac_f32_e32 v142, 0.5, v128
	v_lshlrev_b32_e32 v128, 16, v136
	v_fmac_f32_e32 v143, 0.5, v129
	v_and_b32_e32 v129, 0xffff0000, v136
	v_fmac_f32_e32 v186, v128, v128
	v_cvt_pk_bf16_f32 v137, v142, v143
	v_fmac_f32_e32 v186, v129, v129
	v_lshlrev_b32_e32 v130, 16, v137
	v_pk_add_f32 v[140:141], v[18:19], v[180:181]
	v_pk_add_f32 v[138:139], v[16:17], v[178:179]
	v_and_b32_e32 v131, 0xffff0000, v137
	v_fmac_f32_e32 v186, v130, v130
	v_fmac_f32_e32 v187, 0.5, v138
	v_fmac_f32_e32 v188, 0.5, v139
	v_cvt_pk_bf16_f32 v138, v187, v188
	v_fmac_f32_e32 v189, 0.5, v140
	v_lshlrev_b32_e32 v140, 16, v138
	v_fmac_f32_e32 v186, v131, v131
	v_fmac_f32_e32 v190, 0.5, v141
	v_and_b32_e32 v141, 0xffff0000, v138
	v_fmac_f32_e32 v186, v140, v140
	v_cvt_pk_bf16_f32 v139, v189, v190
	v_fmac_f32_e32 v186, v141, v141
	v_lshlrev_b32_e32 v142, 16, v139
	v_and_b32_e32 v143, 0xffff0000, v139
	v_fmac_f32_e32 v186, v142, v142
	v_fmac_f32_e32 v186, v143, v143
	ds_bpermute_b32 v128, v237, v186
	v_lshl_add_u64 v[130:131], s[28:29], 0, v[176:177]
	v_lshl_add_u64 v[130:131], v[168:169], 1, v[130:131]
	global_store_dwordx4 v[130:131], v[132:135], off
	global_store_dwordx4 v[130:131], v[136:139], off offset:256
	s_waitcnt lgkmcnt(0)
	v_add_f32_e32 v128, v186, v128
	ds_bpermute_b32 v129, v238, v128
	s_and_saveexec_b64 s[12:13], s[8:9]
	s_cbranch_execz .LBB0_1422
	s_waitcnt lgkmcnt(0)
	v_add_f32_e32 v130, v128, v129
	v_lshl_add_u64 v[128:129], v[166:167], 2, s[14:15]
	global_atomic_add_f32 v[128:129], v130, off offset:576

; DI unsigned cvt_pk(float lo, float hi) { unsigned r; asm("v_cvt_pk_bf16_f32 %0, %1, %2" : "=v"(r) : "v"(lo), "v"(hi)); return r; }
;     __device__ __forceinline__ void operator()(const f32x4 (&acc)[2][2][4][2], const Unit& u, int wr, int wc, int fr, int fq) const {
;     ...
; #pragma unroll
;                 for (int mm = 0; mm < 2; ++mm) {
;                     const int m = mp * 2 + mm;
;                     const int row = row0 + ai * HALF + m * 16;
;                     float s = 0.f;
; #pragma unroll
;                     for (int bj = 0; bj < 2; ++bj) {
;                         u32x4* px = (u32x4*)(X + (size_t)row * DM + col0 + bj * HALF);
;                         float xo[8]; unpack8(xin[mm][bj], xo);
;                         const f32x4 a0 = acc[ai][bj][m][0] + pv[mm][bj][0], a1 = acc[ai][bj][m][1] + pv[mm][bj][1];
;                         u32x4 w;
;                         w.x = cvt_pk(xo[0] + scale * a0[0], xo[1] + scale * a0[1]); w.y = cvt_pk(xo[2] + scale * a0[2], xo[3] + scale * a0[3]);
;                         w.z = cvt_pk(xo[4] + scale * a1[0], xo[5] + scale * a1[1]); w.w = cvt_pk(xo[6] + scale * a1[2], xo[7] + scale * a1[3]);
;                         *px = w;
;                         float xn[8]; unpack8(w, xn);
; #pragma unroll
;                         for (int j = 0; j < 8; ++j) s += xn[j] * xn[j];
;                     }
;                     s += __shfl_xor(s, 16); s += __shfl_xor(s, 32);
;                     if (fq == 0) unsafeAtomicAdd(ssn + row, s);
;                 }
.LBB0_1424:
	s_or_b64 exec, exec, s[12:13]
	v_lshlrev_b32_e32 v208, 16, v140
	v_and_b32_e32 v209, 0xffff0000, v140
	v_lshlrev_b32_e32 v210, 16, v141
	v_and_b32_e32 v211, 0xffff0000, v141
	v_and_b32_e32 v245, 0xffff0000, v143
	v_pk_add_f32 v[140:141], v[44:45], v[204:205]
	v_pk_add_f32 v[170:171], v[42:43], v[202:203]
	v_lshlrev_b32_e32 v244, 16, v143
	v_fmac_f32_e32 v208, 0.5, v140
	v_fmac_f32_e32 v209, 0.5, v141
	v_cvt_pk_bf16_f32 v140, v208, v209
	v_fmac_f32_e32 v245, 0.5, v171
	v_and_b32_e32 v171, 0xffff0000, v140
	v_lshlrev_b32_e32 v214, 16, v142
	v_and_b32_e32 v215, 0xffff0000, v142
	v_pk_add_f32 v[142:143], v[46:47], v[206:207]
	v_pk_add_f32 v[200:201], v[40:41], v[200:201]
	v_fmac_f32_e32 v244, 0.5, v170
	v_lshlrev_b32_e32 v170, 16, v140
	v_mul_f32_e32 v206, v171, v171
	v_fmac_f32_e32 v210, 0.5, v142
	v_fmac_f32_e32 v211, 0.5, v143
	v_cvt_pk_bf16_f32 v141, v210, v211
	v_fmac_f32_e32 v214, 0.5, v200
	v_lshlrev_b32_e32 v200, 16, v141
	v_fmac_f32_e32 v206, v170, v170
	v_fmac_f32_e32 v215, 0.5, v201
	v_and_b32_e32 v201, 0xffff0000, v141
	v_fmac_f32_e32 v206, v200, v200
	v_cvt_pk_bf16_f32 v142, v214, v215
	v_fmac_f32_e32 v206, v201, v201
	v_lshlrev_b32_e32 v202, 16, v142
	v_and_b32_e32 v203, 0xffff0000, v142
	v_fmac_f32_e32 v206, v202, v202
	v_cvt_pk_bf16_f32 v143, v244, v245
	v_fmac_f32_e32 v206, v203, v203
	v_lshlrev_b32_e32 v204, 16, v143
	v_and_b32_e32 v205, 0xffff0000, v143
	v_fmac_f32_e32 v206, v204, v204
	v_fmac_f32_e32 v206, v205, v205
	v_lshlrev_b32_e32 v200, 16, v136
	v_and_b32_e32 v201, 0xffff0000, v136
	v_lshlrev_b32_e32 v202, 16, v137
	v_and_b32_e32 v203, 0xffff0000, v137
	v_lshlrev_b32_e32 v204, 16, v138
	v_and_b32_e32 v205, 0xffff0000, v138
	v_lshlrev_b32_e32 v207, 16, v139
	v_and_b32_e32 v208, 0xffff0000, v139
	v_pk_add_f32 v[136:137], v[14:15], v[198:199]
	v_pk_add_f32 v[138:139], v[12:13], v[196:197]
	v_pk_add_f32 v[170:171], v[10:11], v[194:195]
	v_pk_add_f32 v[194:195], v[8:9], v[192:193]
	v_fmac_f32_e32 v200, 0.5, v138
	v_fmac_f32_e32 v201, 0.5, v139
	v_cvt_pk_bf16_f32 v192, v200, v201
	v_fmac_f32_e32 v202, 0.5, v136
	v_lshlrev_b32_e32 v136, 16, v192
	v_fmac_f32_e32 v203, 0.5, v137
	v_and_b32_e32 v137, 0xffff0000, v192
	v_fmac_f32_e32 v206, v136, v136
	v_cvt_pk_bf16_f32 v193, v202, v203
	v_fmac_f32_e32 v206, v137, v137
	v_lshlrev_b32_e32 v138, 16, v193
	v_and_b32_e32 v139, 0xffff0000, v193
	v_fmac_f32_e32 v206, v138, v138
	v_fmac_f32_e32 v204, 0.5, v194
	v_fmac_f32_e32 v205, 0.5, v195
	v_cvt_pk_bf16_f32 v194, v204, v205
	v_fmac_f32_e32 v207, 0.5, v170
	v_lshlrev_b32_e32 v170, 16, v194
	v_fmac_f32_e32 v206, v139, v139
	v_fmac_f32_e32 v208, 0.5, v171
	v_and_b32_e32 v171, 0xffff0000, v194
	v_fmac_f32_e32 v206, v170, v170
	v_cvt_pk_bf16_f32 v195, v207, v208
	v_fmac_f32_e32 v206, v171, v171
	v_lshlrev_b32_e32 v196, 16, v195
	v_and_b32_e32 v197, 0xffff0000, v195
	v_fmac_f32_e32 v206, v196, v196
	v_fmac_f32_e32 v206, v197, v197
	ds_bpermute_b32 v136, v237, v206
	v_lshl_add_u64 v[138:139], s[28:29], 0, v[182:183]
	v_lshl_add_u64 v[138:139], v[168:169], 1, v[138:139]
	global_store_dwordx4 v[138:139], v[140:143], off
	global_store_dwordx4 v[138:139], v[192:195], off offset:256
	s_waitcnt lgkmcnt(0)
	v_add_f32_e32 v136, v206, v136
	ds_bpermute_b32 v137, v238, v136
	s_and_saveexec_b64 s[12:13], s[8:9]
	s_cbranch_execz .LBB0_1426
	s_waitcnt lgkmcnt(0)
	v_add_f32_e32 v138, v136, v137
	v_lshl_add_u64 v[136:137], v[166:167], 2, s[14:15]
	global_atomic_add_f32 v[136:137], v138, off offset:640
.LBB0_1426:
	s_or_b64 exec, exec, s[12:13]
	v_lshlrev_b32_e32 v140, 16, v132
	v_and_b32_e32 v141, 0xffff0000, v132
	v_lshlrev_b32_e32 v142, 16, v133
	v_and_b32_e32 v143, 0xffff0000, v133
	v_lshlrev_b32_e32 v170, 16, v134
	v_and_b32_e32 v183, 0xffff0000, v135
	v_pk_add_f32 v[132:133], v[36:37], v[188:189]
	s_waitcnt lgkmcnt(0)
	v_pk_add_f32 v[136:137], v[34:35], v[186:187]
	v_pk_add_f32 v[138:139], v[32:33], v[184:185]
	v_and_b32_e32 v171, 0xffff0000, v134
	v_lshlrev_b32_e32 v182, 16, v135
	v_pk_add_f32 v[134:135], v[38:39], v[190:191]
	v_fmac_f32_e32 v140, 0.5, v132
	v_fmac_f32_e32 v141, 0.5, v133
	v_cvt_pk_bf16_f32 v132, v140, v141
	v_fmac_f32_e32 v170, 0.5, v138
	v_fmac_f32_e32 v183, 0.5, v137
	v_and_b32_e32 v137, 0xffff0000, v132
	v_fmac_f32_e32 v142, 0.5, v134
	v_fmac_f32_e32 v171, 0.5, v139
	v_cvt_pk_bf16_f32 v134, v170, v171
	v_fmac_f32_e32 v182, 0.5, v136
	v_lshlrev_b32_e32 v136, 16, v132
	v_mul_f32_e32 v170, v137, v137
	v_fmac_f32_e32 v143, 0.5, v135
	v_cvt_pk_bf16_f32 v133, v142, v143
	v_fmac_f32_e32 v170, v136, v136
	v_lshlrev_b32_e32 v138, 16, v133
	v_and_b32_e32 v139, 0xffff0000, v133
	v_fmac_f32_e32 v170, v138, v138
	v_lshlrev_b32_e32 v140, 16, v134
	v_fmac_f32_e32 v170, v139, v139
	v_and_b32_e32 v141, 0xffff0000, v134
	v_fmac_f32_e32 v170, v140, v140
	v_cvt_pk_bf16_f32 v135, v182, v183
	v_fmac_f32_e32 v170, v141, v141
	v_lshlrev_b32_e32 v142, 16, v135
	v_and_b32_e32 v143, 0xffff0000, v135
	v_fmac_f32_e32 v170, v142, v142
	v_lshlrev_b32_e32 v136, 16, v128
	v_lshlrev_b32_e32 v171, 16, v130
	v_and_b32_e32 v182, 0xffff0000, v130
	v_lshlrev_b32_e32 v183, 16, v131
	v_and_b32_e32 v184, 0xffff0000, v131
	v_pk_add_f32 v[130:131], v[4:5], v[178:179]
	v_fmac_f32_e32 v170, v143, v143
	v_and_b32_e32 v137, 0xffff0000, v128
	v_lshlrev_b32_e32 v142, 16, v129
	v_and_b32_e32 v143, 0xffff0000, v129
	v_pk_add_f32 v[128:129], v[6:7], v[180:181]
	v_fmac_f32_e32 v136, 0.5, v130
	v_fmac_f32_e32 v137, 0.5, v131
	v_cvt_pk_bf16_f32 v136, v136, v137
	v_fmac_f32_e32 v142, 0.5, v128
	v_lshlrev_b32_e32 v128, 16, v136
	v_fmac_f32_e32 v143, 0.5, v129
	v_and_b32_e32 v129, 0xffff0000, v136
	v_fmac_f32_e32 v170, v128, v128
	v_cvt_pk_bf16_f32 v137, v142, v143
	v_fmac_f32_e32 v170, v129, v129
	v_lshlrev_b32_e32 v130, 16, v137
	v_pk_add_f32 v[140:141], v[2:3], v[176:177]
	v_pk_add_f32 v[138:139], v[0:1], v[172:173]
	v_and_b32_e32 v131, 0xffff0000, v137
	v_fmac_f32_e32 v170, v130, v130
	v_fmac_f32_e32 v171, 0.5, v138
	v_fmac_f32_e32 v182, 0.5, v139
	v_cvt_pk_bf16_f32 v138, v171, v182
	v_fmac_f32_e32 v183, 0.5, v140
	v_lshlrev_b32_e32 v140, 16, v138
	v_fmac_f32_e32 v170, v131, v131
	v_fmac_f32_e32 v184, 0.5, v141
	v_and_b32_e32 v141, 0xffff0000, v138
	v_fmac_f32_e32 v170, v140, v140
	v_cvt_pk_bf16_f32 v139, v183, v184
	v_fmac_f32_e32 v170, v141, v141
	v_lshlrev_b32_e32 v142, 16, v139
	v_and_b32_e32 v143, 0xffff0000, v139
	v_fmac_f32_e32 v170, v142, v142
	v_fmac_f32_e32 v170, v143, v143
	ds_bpermute_b32 v128, v237, v170
	v_lshl_add_u64 v[130:131], s[28:29], 0, v[174:175]
	v_lshl_add_u64 v[130:131], v[168:169], 1, v[130:131]
	global_store_dwordx4 v[130:131], v[132:135], off
	global_store_dwordx4 v[130:131], v[136:139], off offset:256
	s_waitcnt lgkmcnt(0)
	v_add_f32_e32 v128, v170, v128
	ds_bpermute_b32 v129, v238, v128
	s_and_saveexec_b64 s[12:13], s[8:9]
	s_cbranch_execz .LBB0_1428
	s_waitcnt lgkmcnt(0)
	v_add_f32_e32 v130, v128, v129
	v_lshl_add_u64 v[128:129], v[166:167], 2, s[14:15]
	global_atomic_add_f32 v[128:129], v130, off offset:704
